# all six GEMM K-loops: first iteration peeled with SrcC=0 on each accumulator's first MFMA; per-unit accumulator zeroing (95-127 v_mov) removed
# baseline (speedup 1.0000x reference)
.LBB0_258:
	s_mov_b32 s24, s21
	s_mov_b32 s20, s25
	s_ashr_i32 s25, s21, 31
	s_xor_b64 s[60:61], s[26:27], -1
	s_lshl_b64 s[12:13], s[24:25], 20
	s_add_u32 s12, s18, s12
	s_addc_u32 s13, s19, s13
	s_cmp_gt_i32 s33, 0
	s_cselect_b32 s14, 0x80000, 0
	s_add_u32 s48, s12, s14
	s_addc_u32 s49, s13, 0
	s_and_b64 s[12:13], s[36:37], exec
	s_mov_b32 s71, s33
	s_cselect_b32 s25, s49, s59
	s_cselect_b32 s33, s48, s58
	s_ashr_i32 s21, s20, 31
	s_lshl_b64 s[12:13], s[20:21], 20
	s_add_u32 s54, s22, s12
	s_addc_u32 s55, s23, s13
	s_and_b64 s[12:13], s[36:37], exec
	s_cselect_b32 s21, s55, s51
	s_cselect_b32 s73, s54, s50
	s_cmp_gt_i32 s71, -1
	s_cselect_b64 s[56:57], -1, 0
	s_add_u32 s12, s58, 0x80
	v_cndmask_b32_e64 v2, 0, 1, s[56:57]
	v_cndmask_b32_e64 v8, 0, 1, s[26:27]
	s_addc_u32 s13, s59, 0
	v_cndmask_b32_e64 v2, v8, v2, s[36:37]
	v_lshl_add_u64 v[8:9], s[12:13], 0, v[214:215]
	v_and_b32_e32 v2, 1, v2
	v_lshl_add_u64 v[220:221], v[8:9], 0, v[218:219]
	v_lshl_add_u64 v[8:9], s[12:13], 0, v[216:217]
	v_cmp_eq_u32_e32 vcc, 1, v2
	v_lshl_add_u64 v[222:223], v[8:9], 0, v[218:219]
	s_add_u32 s26, s50, 0x100
	v_cndmask_b32_e64 v2, v246, 0, vcc
	s_addc_u32 s27, s51, 0
	s_mov_b32 s74, -2
	s_mov_b64 s[62:63], 0
	v_add_u32_e32 v168, 0x10000, v232
	v_add_u32_e32 v180, 0x14000, v232
	v_lshl_add_u64 v[224:225], v[222:223], 0, s[62:63]
	s_add_i32 m0, s35, 0xc000
	s_waitcnt lgkmcnt(0)
	ds_read_b128 v[148:151], v207
	ds_read_b128 v[164:167], v207 offset:1024
	ds_read_b128 v[144:147], v207 offset:2048
	ds_read_b128 v[160:163], v207 offset:3072
	ds_read_b128 v[140:143], v207 offset:4096
	ds_read_b128 v[156:159], v207 offset:5120
	ds_read_b128 v[136:139], v207 offset:6144
	ds_read_b128 v[152:155], v207 offset:7168
	ds_read_b128 v[184:187], v168
	ds_read_b128 v[188:191], v168 offset:1024
	ds_read_b128 v[192:195], v168 offset:2048
	ds_read_b128 v[196:199], v168 offset:3072
	ds_read_b128 v[168:171], v180
	ds_read_b128 v[172:175], v180 offset:1024
	ds_read_b128 v[176:179], v180 offset:2048
	ds_read_b128 v[180:183], v180 offset:3072
	global_load_lds_dwordx4 v[224:225], off
	v_lshl_add_u64 v[224:225], v[220:221], 0, s[62:63]
	s_add_i32 m0, s35, 0xe000
	s_nop 0
	global_load_lds_dwordx4 v[224:225], off
	s_waitcnt vmcnt(8)
	s_waitcnt lgkmcnt(0)
	s_barrier
	s_waitcnt lgkmcnt(0)
	v_mfma_f32_16x16x32_bf16 v[132:135], v[184:187], v[148:151], 0
	v_mfma_f32_16x16x32_bf16 v[132:135], v[188:191], v[164:167], v[132:135]
	v_mfma_f32_16x16x32_bf16 v[128:131], v[192:195], v[148:151], 0
	v_mfma_f32_16x16x32_bf16 v[128:131], v[196:199], v[164:167], v[128:131]
	v_mfma_f32_16x16x32_bf16 v[124:127], v[168:171], v[148:151], 0
	v_mfma_f32_16x16x32_bf16 v[124:127], v[172:175], v[164:167], v[124:127]
	v_mfma_f32_16x16x32_bf16 v[120:123], v[176:179], v[148:151], 0
	v_mfma_f32_16x16x32_bf16 v[120:123], v[180:183], v[164:167], v[120:123]
	v_mfma_f32_16x16x32_bf16 v[116:119], v[184:187], v[144:147], 0
	v_mfma_f32_16x16x32_bf16 v[116:119], v[188:191], v[160:163], v[116:119]
	v_mfma_f32_16x16x32_bf16 v[112:115], v[192:195], v[144:147], 0
	v_mfma_f32_16x16x32_bf16 v[112:115], v[196:199], v[160:163], v[112:115]
	v_mfma_f32_16x16x32_bf16 v[108:111], v[168:171], v[144:147], 0
	v_mfma_f32_16x16x32_bf16 v[108:111], v[172:175], v[160:163], v[108:111]
	v_mfma_f32_16x16x32_bf16 v[104:107], v[176:179], v[144:147], 0
	v_mfma_f32_16x16x32_bf16 v[104:107], v[180:183], v[160:163], v[104:107]
	v_mfma_f32_16x16x32_bf16 v[100:103], v[184:187], v[140:143], 0
	v_mfma_f32_16x16x32_bf16 v[100:103], v[188:191], v[156:159], v[100:103]
	v_mfma_f32_16x16x32_bf16 v[96:99], v[192:195], v[140:143], 0
	v_mfma_f32_16x16x32_bf16 v[96:99], v[196:199], v[156:159], v[96:99]
	v_mfma_f32_16x16x32_bf16 v[92:95], v[168:171], v[140:143], 0
	v_mfma_f32_16x16x32_bf16 v[92:95], v[172:175], v[156:159], v[92:95]
	v_mfma_f32_16x16x32_bf16 v[88:91], v[176:179], v[140:143], 0
	v_mfma_f32_16x16x32_bf16 v[88:91], v[180:183], v[156:159], v[88:91]
	v_mfma_f32_16x16x32_bf16 v[84:87], v[184:187], v[136:139], 0
	v_mfma_f32_16x16x32_bf16 v[84:87], v[188:191], v[152:155], v[84:87]
	v_mfma_f32_16x16x32_bf16 v[80:83], v[192:195], v[136:139], 0
	v_mfma_f32_16x16x32_bf16 v[80:83], v[196:199], v[152:155], v[80:83]
	v_mfma_f32_16x16x32_bf16 v[76:79], v[168:171], v[136:139], 0
	v_mfma_f32_16x16x32_bf16 v[76:79], v[172:175], v[152:155], v[76:79]
	v_mfma_f32_16x16x32_bf16 v[72:75], v[176:179], v[136:139], 0
	v_mfma_f32_16x16x32_bf16 v[72:75], v[180:183], v[152:155], v[72:75]
	s_barrier
	v_cndmask_b32_e64 v204, 0, 1, s[60:61]
	v_cmp_ne_u32_e64 s[50:51], 1, v204
	s_andn2_b64 vcc, exec, s[60:61]
	s_cbranch_vccnz .Lpeel0_262
	ds_read_b128 v[148:151], v207 offset:16384
	ds_read_b128 v[164:167], v207 offset:17408
	ds_read_b128 v[144:147], v207 offset:18432
	ds_read_b128 v[160:163], v207 offset:19456
	ds_read_b128 v[140:143], v207 offset:20480
	ds_read_b128 v[156:159], v207 offset:21504
	ds_read_b128 v[136:139], v207 offset:22528
	ds_read_b128 v[152:155], v207 offset:23552
.Lpeel0_262:
	s_add_u32 s12, s58, s62
	s_addc_u32 s13, s59, s63
	s_add_u32 s14, s12, 0x100
	s_addc_u32 s15, s13, 0
	s_add_u32 s75, s26, s62
	s_addc_u32 s76, s27, s63
	s_cmpk_eq_i32 s62, 0xf00
	s_cselect_b64 s[52:53], -1, 0
	s_and_b64 s[12:13], s[52:53], exec
	s_cselect_b32 s13, s21, s76
	s_cselect_b32 s12, s73, s75
	s_mov_b32 m0, s38
	s_cselect_b32 s15, s25, s15
	s_cselect_b32 s14, s33, s14
	v_lshl_add_u64 v[224:225], s[12:13], 0, v[208:209]
	s_add_u32 s76, s12, 0x80000
	global_load_lds_dwordx4 v[224:225], off
	v_lshl_add_u64 v[226:227], s[12:13], 0, v[212:213]
	s_mov_b32 m0, s39
	s_addc_u32 s77, s13, 0
	global_load_lds_dwordx4 v[226:227], off
	v_lshl_add_u64 v[228:229], s[76:77], 0, v[208:209]
	s_mov_b32 m0, s40
	v_lshl_add_u64 v[230:231], s[14:15], 0, v[210:211]
	global_load_lds_dwordx4 v[228:229], off
	v_lshl_add_u64 v[228:229], s[76:77], 0, v[212:213]
	s_mov_b32 m0, s41
	s_and_b64 vcc, exec, s[50:51]
	global_load_lds_dwordx4 v[228:229], off
	v_lshl_add_u64 v[228:229], s[14:15], 0, v[4:5]
	s_mov_b32 m0, s35
	s_nop 0
	global_load_lds_dwordx4 v[228:229], off
	s_mov_b32 m0, s43
	s_nop 0
	global_load_lds_dwordx4 v[230:231], off
	s_waitcnt vmcnt(8)
	s_waitcnt lgkmcnt(0)
	s_barrier
	s_cbranch_vccnz .Lpeel0_264
	s_waitcnt lgkmcnt(0)
	v_mfma_f32_16x16x32_bf16 v[68:71], v[184:187], v[148:151], 0
	v_mfma_f32_16x16x32_bf16 v[68:71], v[188:191], v[164:167], v[68:71]
	v_mfma_f32_16x16x32_bf16 v[64:67], v[192:195], v[148:151], 0
	v_mfma_f32_16x16x32_bf16 v[64:67], v[196:199], v[164:167], v[64:67]
	v_mfma_f32_16x16x32_bf16 v[60:63], v[168:171], v[148:151], 0
	v_mfma_f32_16x16x32_bf16 v[60:63], v[172:175], v[164:167], v[60:63]
	v_mfma_f32_16x16x32_bf16 v[56:59], v[176:179], v[148:151], 0
	v_mfma_f32_16x16x32_bf16 v[56:59], v[180:183], v[164:167], v[56:59]
	v_mfma_f32_16x16x32_bf16 v[52:55], v[184:187], v[144:147], 0
	v_mfma_f32_16x16x32_bf16 v[52:55], v[188:191], v[160:163], v[52:55]
	v_mfma_f32_16x16x32_bf16 v[48:51], v[192:195], v[144:147], 0
	v_mfma_f32_16x16x32_bf16 v[48:51], v[196:199], v[160:163], v[48:51]
	v_mfma_f32_16x16x32_bf16 v[44:47], v[168:171], v[144:147], 0
	v_mfma_f32_16x16x32_bf16 v[44:47], v[172:175], v[160:163], v[44:47]
	v_mfma_f32_16x16x32_bf16 v[40:43], v[176:179], v[144:147], 0
	v_mfma_f32_16x16x32_bf16 v[40:43], v[180:183], v[160:163], v[40:43]
	v_mfma_f32_16x16x32_bf16 v[36:39], v[184:187], v[140:143], 0
	v_mfma_f32_16x16x32_bf16 v[36:39], v[188:191], v[156:159], v[36:39]
	v_mfma_f32_16x16x32_bf16 v[32:35], v[192:195], v[140:143], 0
	v_mfma_f32_16x16x32_bf16 v[32:35], v[196:199], v[156:159], v[32:35]
	v_mfma_f32_16x16x32_bf16 v[28:31], v[168:171], v[140:143], 0
	v_mfma_f32_16x16x32_bf16 v[28:31], v[172:175], v[156:159], v[28:31]
	v_mfma_f32_16x16x32_bf16 v[24:27], v[176:179], v[140:143], 0
	v_mfma_f32_16x16x32_bf16 v[24:27], v[180:183], v[156:159], v[24:27]
	v_mfma_f32_16x16x32_bf16 v[20:23], v[184:187], v[136:139], 0
	v_mfma_f32_16x16x32_bf16 v[20:23], v[188:191], v[152:155], v[20:23]
	v_mfma_f32_16x16x32_bf16 v[16:19], v[192:195], v[136:139], 0
	v_mfma_f32_16x16x32_bf16 v[16:19], v[196:199], v[152:155], v[16:19]
	v_mfma_f32_16x16x32_bf16 v[12:15], v[168:171], v[136:139], 0
	v_mfma_f32_16x16x32_bf16 v[12:15], v[172:175], v[152:155], v[12:15]
	v_mfma_f32_16x16x32_bf16 v[8:11], v[176:179], v[136:139], 0
	v_mfma_f32_16x16x32_bf16 v[8:11], v[180:183], v[152:155], v[8:11]

.Lpeel0_266:
	s_mov_b32 m0, s64
	v_lshl_add_u64 v[224:225], v[224:225], 0, s[0:1]
	s_add_u32 s12, s12, 0x80080
	global_load_lds_dwordx4 v[224:225], off
	v_lshl_add_u64 v[224:225], v[226:227], 0, s[0:1]
	s_mov_b32 m0, s65
	s_addc_u32 s13, s13, 0
	global_load_lds_dwordx4 v[224:225], off
	v_lshl_add_u64 v[224:225], s[12:13], 0, v[208:209]
	s_mov_b32 m0, s68
	s_and_b64 vcc, exec, s[50:51]
	global_load_lds_dwordx4 v[224:225], off
	v_lshl_add_u64 v[224:225], s[12:13], 0, v[212:213]
	s_mov_b32 m0, s69
	s_nop 0
	global_load_lds_dwordx4 v[224:225], off
	v_lshl_add_u64 v[224:225], v[228:229], 0, s[0:1]
	s_mov_b32 m0, s66
	s_nop 0
	global_load_lds_dwordx4 v[224:225], off
	v_lshl_add_u64 v[224:225], v[230:231], 0, s[0:1]
	s_mov_b32 m0, s67
	s_nop 0
	global_load_lds_dwordx4 v[224:225], off
	s_waitcnt vmcnt(8)
	s_waitcnt lgkmcnt(0)
	s_barrier
	s_cbranch_vccnz .LBB0_259
	s_waitcnt lgkmcnt(0)
	v_mfma_f32_16x16x32_bf16 v[68:71], v[184:187], v[148:151], v[68:71]
	v_mfma_f32_16x16x32_bf16 v[68:71], v[188:191], v[164:167], v[68:71]
	v_mfma_f32_16x16x32_bf16 v[64:67], v[192:195], v[148:151], v[64:67]
	v_mfma_f32_16x16x32_bf16 v[64:67], v[196:199], v[164:167], v[64:67]
	v_mfma_f32_16x16x32_bf16 v[60:63], v[168:171], v[148:151], v[60:63]
	v_mfma_f32_16x16x32_bf16 v[60:63], v[172:175], v[164:167], v[60:63]
	v_mfma_f32_16x16x32_bf16 v[56:59], v[176:179], v[148:151], v[56:59]
	v_mfma_f32_16x16x32_bf16 v[56:59], v[180:183], v[164:167], v[56:59]
	v_mfma_f32_16x16x32_bf16 v[52:55], v[184:187], v[144:147], v[52:55]
	v_mfma_f32_16x16x32_bf16 v[52:55], v[188:191], v[160:163], v[52:55]
	v_mfma_f32_16x16x32_bf16 v[48:51], v[192:195], v[144:147], v[48:51]
	v_mfma_f32_16x16x32_bf16 v[48:51], v[196:199], v[160:163], v[48:51]
	v_mfma_f32_16x16x32_bf16 v[44:47], v[168:171], v[144:147], v[44:47]
	v_mfma_f32_16x16x32_bf16 v[44:47], v[172:175], v[160:163], v[44:47]
	v_mfma_f32_16x16x32_bf16 v[40:43], v[176:179], v[144:147], v[40:43]
	v_mfma_f32_16x16x32_bf16 v[40:43], v[180:183], v[160:163], v[40:43]
	v_mfma_f32_16x16x32_bf16 v[36:39], v[184:187], v[140:143], v[36:39]
	v_mfma_f32_16x16x32_bf16 v[36:39], v[188:191], v[156:159], v[36:39]
	v_mfma_f32_16x16x32_bf16 v[32:35], v[192:195], v[140:143], v[32:35]
	v_mfma_f32_16x16x32_bf16 v[32:35], v[196:199], v[156:159], v[32:35]
	v_mfma_f32_16x16x32_bf16 v[28:31], v[168:171], v[140:143], v[28:31]
	v_mfma_f32_16x16x32_bf16 v[28:31], v[172:175], v[156:159], v[28:31]
	v_mfma_f32_16x16x32_bf16 v[24:27], v[176:179], v[140:143], v[24:27]
	v_mfma_f32_16x16x32_bf16 v[24:27], v[180:183], v[156:159], v[24:27]
	v_mfma_f32_16x16x32_bf16 v[20:23], v[184:187], v[136:139], v[20:23]
	v_mfma_f32_16x16x32_bf16 v[20:23], v[188:191], v[152:155], v[20:23]
	v_mfma_f32_16x16x32_bf16 v[16:19], v[192:195], v[136:139], v[16:19]
	v_mfma_f32_16x16x32_bf16 v[16:19], v[196:199], v[152:155], v[16:19]
	v_mfma_f32_16x16x32_bf16 v[12:15], v[168:171], v[136:139], v[12:15]
	v_mfma_f32_16x16x32_bf16 v[12:15], v[172:175], v[152:155], v[12:15]
	v_mfma_f32_16x16x32_bf16 v[8:11], v[176:179], v[136:139], v[8:11]
	v_mfma_f32_16x16x32_bf16 v[8:11], v[180:183], v[152:155], v[8:11]
	s_branch .LBB0_259
.LBB0_259:
	s_barrier
	s_add_i32 s74, s74, 2
	s_add_u32 s62, s62, 0x100
	s_addc_u32 s63, s63, 0
	s_cmp_gt_u32 s74, 29
	s_cbranch_scc1 .LBB0_268

.LBB0_367:
	s_mov_b32 s42, s7
	s_ashr_i32 s43, s7, 31
	s_xor_b64 s[58:59], s[26:27], -1
	s_lshl_b64 s[12:13], s[42:43], 20
	s_add_u32 s7, s18, s12
	s_addc_u32 s12, s19, s13
	s_cmp_gt_i32 s37, 0
	s_cselect_b32 s13, 0x80000, 0
	s_add_u32 s48, s7, s13
	s_addc_u32 s49, s12, 0
	s_mov_b32 s36, s33
	s_and_b64 s[12:13], s[44:45], exec
	s_mov_b32 s71, s37
	s_cselect_b32 s7, s49, s25
	s_cselect_b32 s33, s48, s24
	s_ashr_i32 s37, s36, 31
	s_lshl_b64 s[12:13], s[36:37], 20
	s_add_u32 s54, s22, s12
	s_addc_u32 s55, s23, s13
	s_and_b64 s[12:13], s[44:45], exec
	s_cselect_b32 s37, s55, s51
	s_cselect_b32 s43, s54, s50
	s_cmp_gt_i32 s71, -1
	s_cselect_b64 s[56:57], -1, 0
	s_add_u32 s12, s24, 0x80
	v_cndmask_b32_e64 v2, 0, 1, s[56:57]
	v_cndmask_b32_e64 v8, 0, 1, s[26:27]
	s_addc_u32 s13, s25, 0
	v_cndmask_b32_e64 v2, v8, v2, s[44:45]
	v_lshl_add_u64 v[8:9], s[12:13], 0, v[214:215]
	v_and_b32_e32 v2, 1, v2
	v_lshl_add_u64 v[220:221], v[8:9], 0, v[218:219]
	v_lshl_add_u64 v[8:9], s[12:13], 0, v[216:217]
	v_cmp_eq_u32_e32 vcc, 1, v2
	v_lshl_add_u64 v[222:223], v[8:9], 0, v[218:219]
	s_add_u32 s26, s50, 0x100
	v_cndmask_b32_e64 v2, v246, 0, vcc
	s_addc_u32 s27, s51, 0
	s_mov_b32 s72, -2
	s_mov_b64 s[60:61], 0
	v_add_u32_e32 v168, 0x10000, v232
	v_add_u32_e32 v180, 0x14000, v232
	v_lshl_add_u64 v[224:225], v[222:223], 0, s[60:61]
	s_add_i32 m0, s9, 0xc000
	s_waitcnt lgkmcnt(0)
	ds_read_b128 v[148:151], v207
	ds_read_b128 v[164:167], v207 offset:1024
	ds_read_b128 v[144:147], v207 offset:2048
	ds_read_b128 v[160:163], v207 offset:3072
	ds_read_b128 v[140:143], v207 offset:4096
	ds_read_b128 v[156:159], v207 offset:5120
	ds_read_b128 v[136:139], v207 offset:6144
	ds_read_b128 v[152:155], v207 offset:7168
	ds_read_b128 v[184:187], v168
	ds_read_b128 v[188:191], v168 offset:1024
	ds_read_b128 v[192:195], v168 offset:2048
	ds_read_b128 v[196:199], v168 offset:3072
	ds_read_b128 v[168:171], v180
	ds_read_b128 v[172:175], v180 offset:1024
	ds_read_b128 v[176:179], v180 offset:2048
	ds_read_b128 v[180:183], v180 offset:3072
	global_load_lds_dwordx4 v[224:225], off
	v_lshl_add_u64 v[224:225], v[220:221], 0, s[60:61]
	s_add_i32 m0, s9, 0xe000
	s_nop 0
	global_load_lds_dwordx4 v[224:225], off
	s_waitcnt vmcnt(8)
	s_waitcnt lgkmcnt(0)
	s_barrier
	s_waitcnt lgkmcnt(0)
	v_mfma_f32_16x16x32_bf16 v[132:135], v[184:187], v[148:151], 0
	v_mfma_f32_16x16x32_bf16 v[132:135], v[188:191], v[164:167], v[132:135]
	v_mfma_f32_16x16x32_bf16 v[128:131], v[192:195], v[148:151], 0
	v_mfma_f32_16x16x32_bf16 v[128:131], v[196:199], v[164:167], v[128:131]
	v_mfma_f32_16x16x32_bf16 v[116:119], v[168:171], v[148:151], 0
	v_mfma_f32_16x16x32_bf16 v[116:119], v[172:175], v[164:167], v[116:119]
	v_mfma_f32_16x16x32_bf16 v[112:115], v[176:179], v[148:151], 0
	v_mfma_f32_16x16x32_bf16 v[112:115], v[180:183], v[164:167], v[112:115]
	v_mfma_f32_16x16x32_bf16 v[124:127], v[184:187], v[144:147], 0
	v_mfma_f32_16x16x32_bf16 v[124:127], v[188:191], v[160:163], v[124:127]
	v_mfma_f32_16x16x32_bf16 v[120:123], v[192:195], v[144:147], 0
	v_mfma_f32_16x16x32_bf16 v[120:123], v[196:199], v[160:163], v[120:123]
	v_mfma_f32_16x16x32_bf16 v[100:103], v[168:171], v[144:147], 0
	v_mfma_f32_16x16x32_bf16 v[100:103], v[172:175], v[160:163], v[100:103]
	v_mfma_f32_16x16x32_bf16 v[96:99], v[176:179], v[144:147], 0
	v_mfma_f32_16x16x32_bf16 v[96:99], v[180:183], v[160:163], v[96:99]
	v_mfma_f32_16x16x32_bf16 v[108:111], v[184:187], v[140:143], 0
	v_mfma_f32_16x16x32_bf16 v[108:111], v[188:191], v[156:159], v[108:111]
	v_mfma_f32_16x16x32_bf16 v[104:107], v[192:195], v[140:143], 0
	v_mfma_f32_16x16x32_bf16 v[104:107], v[196:199], v[156:159], v[104:107]
	v_mfma_f32_16x16x32_bf16 v[84:87], v[168:171], v[140:143], 0
	v_mfma_f32_16x16x32_bf16 v[84:87], v[172:175], v[156:159], v[84:87]
	v_mfma_f32_16x16x32_bf16 v[80:83], v[176:179], v[140:143], 0
	v_mfma_f32_16x16x32_bf16 v[80:83], v[180:183], v[156:159], v[80:83]
	v_mfma_f32_16x16x32_bf16 v[92:95], v[184:187], v[136:139], 0
	v_mfma_f32_16x16x32_bf16 v[92:95], v[188:191], v[152:155], v[92:95]
	v_mfma_f32_16x16x32_bf16 v[88:91], v[192:195], v[136:139], 0
	v_mfma_f32_16x16x32_bf16 v[88:91], v[196:199], v[152:155], v[88:91]
	v_mfma_f32_16x16x32_bf16 v[76:79], v[168:171], v[136:139], 0
	v_mfma_f32_16x16x32_bf16 v[76:79], v[172:175], v[152:155], v[76:79]
	v_mfma_f32_16x16x32_bf16 v[72:75], v[176:179], v[136:139], 0
	v_mfma_f32_16x16x32_bf16 v[72:75], v[180:183], v[152:155], v[72:75]
	s_barrier
	v_cndmask_b32_e64 v204, 0, 1, s[58:59]
	v_cmp_ne_u32_e64 s[50:51], 1, v204
	s_andn2_b64 vcc, exec, s[58:59]
	s_cbranch_vccnz .Lpeel1_371
	ds_read_b128 v[148:151], v207 offset:16384
	ds_read_b128 v[164:167], v207 offset:17408
	ds_read_b128 v[144:147], v207 offset:18432
	ds_read_b128 v[160:163], v207 offset:19456
	ds_read_b128 v[140:143], v207 offset:20480
	ds_read_b128 v[156:159], v207 offset:21504
	ds_read_b128 v[136:139], v207 offset:22528
	ds_read_b128 v[152:155], v207 offset:23552
.Lpeel1_371:
	s_add_u32 s12, s24, s60
	s_addc_u32 s13, s25, s61
	s_add_u32 s14, s12, 0x100
	s_addc_u32 s15, s13, 0
	s_add_u32 s73, s26, s60
	s_addc_u32 s74, s27, s61
	s_cmpk_eq_i32 s60, 0xf00
	s_cselect_b64 s[52:53], -1, 0
	s_and_b64 s[12:13], s[52:53], exec
	s_cselect_b32 s13, s37, s74
	s_cselect_b32 s12, s43, s73
	s_mov_b32 m0, s38
	s_cselect_b32 s15, s7, s15
	s_cselect_b32 s14, s33, s14
	v_lshl_add_u64 v[224:225], s[12:13], 0, v[208:209]
	s_add_u32 s74, s12, 0x80000
	global_load_lds_dwordx4 v[224:225], off
	v_lshl_add_u64 v[226:227], s[12:13], 0, v[212:213]
	s_mov_b32 m0, s39
	s_addc_u32 s75, s13, 0
	global_load_lds_dwordx4 v[226:227], off
	v_lshl_add_u64 v[228:229], s[74:75], 0, v[208:209]
	s_mov_b32 m0, s40
	v_lshl_add_u64 v[230:231], s[14:15], 0, v[210:211]
	global_load_lds_dwordx4 v[228:229], off
	v_lshl_add_u64 v[228:229], s[74:75], 0, v[212:213]
	s_mov_b32 m0, s41
	s_and_b64 vcc, exec, s[50:51]
	global_load_lds_dwordx4 v[228:229], off
	v_lshl_add_u64 v[228:229], s[14:15], 0, v[4:5]
	s_mov_b32 m0, s9
	s_nop 0
	global_load_lds_dwordx4 v[228:229], off
	s_mov_b32 m0, s47
	s_nop 0
	global_load_lds_dwordx4 v[230:231], off
	s_waitcnt vmcnt(8)
	s_waitcnt lgkmcnt(0)
	s_barrier
	s_cbranch_vccnz .Lpeel1_373
	s_waitcnt lgkmcnt(0)
	v_mfma_f32_16x16x32_bf16 v[68:71], v[184:187], v[148:151], 0
	v_mfma_f32_16x16x32_bf16 v[68:71], v[188:191], v[164:167], v[68:71]
	v_mfma_f32_16x16x32_bf16 v[64:67], v[192:195], v[148:151], 0
	v_mfma_f32_16x16x32_bf16 v[64:67], v[196:199], v[164:167], v[64:67]
	v_mfma_f32_16x16x32_bf16 v[60:63], v[168:171], v[148:151], 0
	v_mfma_f32_16x16x32_bf16 v[60:63], v[172:175], v[164:167], v[60:63]
	v_mfma_f32_16x16x32_bf16 v[56:59], v[176:179], v[148:151], 0
	v_mfma_f32_16x16x32_bf16 v[56:59], v[180:183], v[164:167], v[56:59]
	v_mfma_f32_16x16x32_bf16 v[52:55], v[184:187], v[144:147], 0
	v_mfma_f32_16x16x32_bf16 v[52:55], v[188:191], v[160:163], v[52:55]
	v_mfma_f32_16x16x32_bf16 v[48:51], v[192:195], v[144:147], 0
	v_mfma_f32_16x16x32_bf16 v[48:51], v[196:199], v[160:163], v[48:51]
	v_mfma_f32_16x16x32_bf16 v[44:47], v[168:171], v[144:147], 0
	v_mfma_f32_16x16x32_bf16 v[44:47], v[172:175], v[160:163], v[44:47]
	v_mfma_f32_16x16x32_bf16 v[40:43], v[176:179], v[144:147], 0
	v_mfma_f32_16x16x32_bf16 v[40:43], v[180:183], v[160:163], v[40:43]
	v_mfma_f32_16x16x32_bf16 v[36:39], v[184:187], v[140:143], 0
	v_mfma_f32_16x16x32_bf16 v[36:39], v[188:191], v[156:159], v[36:39]
	v_mfma_f32_16x16x32_bf16 v[32:35], v[192:195], v[140:143], 0
	v_mfma_f32_16x16x32_bf16 v[32:35], v[196:199], v[156:159], v[32:35]
	v_mfma_f32_16x16x32_bf16 v[28:31], v[168:171], v[140:143], 0
	v_mfma_f32_16x16x32_bf16 v[28:31], v[172:175], v[156:159], v[28:31]
	v_mfma_f32_16x16x32_bf16 v[24:27], v[176:179], v[140:143], 0
	v_mfma_f32_16x16x32_bf16 v[24:27], v[180:183], v[156:159], v[24:27]
	v_mfma_f32_16x16x32_bf16 v[20:23], v[184:187], v[136:139], 0
	v_mfma_f32_16x16x32_bf16 v[20:23], v[188:191], v[152:155], v[20:23]
	v_mfma_f32_16x16x32_bf16 v[16:19], v[192:195], v[136:139], 0
	v_mfma_f32_16x16x32_bf16 v[16:19], v[196:199], v[152:155], v[16:19]
	v_mfma_f32_16x16x32_bf16 v[12:15], v[168:171], v[136:139], 0
	v_mfma_f32_16x16x32_bf16 v[12:15], v[172:175], v[152:155], v[12:15]
	v_mfma_f32_16x16x32_bf16 v[8:11], v[176:179], v[136:139], 0
	v_mfma_f32_16x16x32_bf16 v[8:11], v[180:183], v[152:155], v[8:11]

.Lpeel1_375:
	s_mov_b32 m0, s64
	v_lshl_add_u64 v[224:225], v[224:225], 0, s[0:1]
	s_add_u32 s12, s12, 0x80080
	global_load_lds_dwordx4 v[224:225], off
	v_lshl_add_u64 v[224:225], v[226:227], 0, s[0:1]
	s_mov_b32 m0, s65
	s_addc_u32 s13, s13, 0
	global_load_lds_dwordx4 v[224:225], off
	v_lshl_add_u64 v[224:225], s[12:13], 0, v[208:209]
	s_mov_b32 m0, s68
	s_and_b64 vcc, exec, s[50:51]
	global_load_lds_dwordx4 v[224:225], off
	v_lshl_add_u64 v[224:225], s[12:13], 0, v[212:213]
	s_mov_b32 m0, s69
	s_nop 0
	global_load_lds_dwordx4 v[224:225], off
	v_lshl_add_u64 v[224:225], v[228:229], 0, s[0:1]
	s_mov_b32 m0, s66
	s_nop 0
	global_load_lds_dwordx4 v[224:225], off
	v_lshl_add_u64 v[224:225], v[230:231], 0, s[0:1]
	s_mov_b32 m0, s67
	s_nop 0
	global_load_lds_dwordx4 v[224:225], off
	s_waitcnt vmcnt(8)
	s_waitcnt lgkmcnt(0)
	s_barrier
	s_cbranch_vccnz .LBB0_368
	s_waitcnt lgkmcnt(0)
	v_mfma_f32_16x16x32_bf16 v[68:71], v[184:187], v[148:151], v[68:71]
	v_mfma_f32_16x16x32_bf16 v[68:71], v[188:191], v[164:167], v[68:71]
	v_mfma_f32_16x16x32_bf16 v[64:67], v[192:195], v[148:151], v[64:67]
	v_mfma_f32_16x16x32_bf16 v[64:67], v[196:199], v[164:167], v[64:67]
	v_mfma_f32_16x16x32_bf16 v[60:63], v[168:171], v[148:151], v[60:63]
	v_mfma_f32_16x16x32_bf16 v[60:63], v[172:175], v[164:167], v[60:63]
	v_mfma_f32_16x16x32_bf16 v[56:59], v[176:179], v[148:151], v[56:59]
	v_mfma_f32_16x16x32_bf16 v[56:59], v[180:183], v[164:167], v[56:59]
	v_mfma_f32_16x16x32_bf16 v[52:55], v[184:187], v[144:147], v[52:55]
	v_mfma_f32_16x16x32_bf16 v[52:55], v[188:191], v[160:163], v[52:55]
	v_mfma_f32_16x16x32_bf16 v[48:51], v[192:195], v[144:147], v[48:51]
	v_mfma_f32_16x16x32_bf16 v[48:51], v[196:199], v[160:163], v[48:51]
	v_mfma_f32_16x16x32_bf16 v[44:47], v[168:171], v[144:147], v[44:47]
	v_mfma_f32_16x16x32_bf16 v[44:47], v[172:175], v[160:163], v[44:47]
	v_mfma_f32_16x16x32_bf16 v[40:43], v[176:179], v[144:147], v[40:43]
	v_mfma_f32_16x16x32_bf16 v[40:43], v[180:183], v[160:163], v[40:43]
	v_mfma_f32_16x16x32_bf16 v[36:39], v[184:187], v[140:143], v[36:39]
	v_mfma_f32_16x16x32_bf16 v[36:39], v[188:191], v[156:159], v[36:39]
	v_mfma_f32_16x16x32_bf16 v[32:35], v[192:195], v[140:143], v[32:35]
	v_mfma_f32_16x16x32_bf16 v[32:35], v[196:199], v[156:159], v[32:35]
	v_mfma_f32_16x16x32_bf16 v[28:31], v[168:171], v[140:143], v[28:31]
	v_mfma_f32_16x16x32_bf16 v[28:31], v[172:175], v[156:159], v[28:31]
	v_mfma_f32_16x16x32_bf16 v[24:27], v[176:179], v[140:143], v[24:27]
	v_mfma_f32_16x16x32_bf16 v[24:27], v[180:183], v[156:159], v[24:27]
	v_mfma_f32_16x16x32_bf16 v[20:23], v[184:187], v[136:139], v[20:23]
	v_mfma_f32_16x16x32_bf16 v[20:23], v[188:191], v[152:155], v[20:23]
	v_mfma_f32_16x16x32_bf16 v[16:19], v[192:195], v[136:139], v[16:19]
	v_mfma_f32_16x16x32_bf16 v[16:19], v[196:199], v[152:155], v[16:19]
	v_mfma_f32_16x16x32_bf16 v[12:15], v[168:171], v[136:139], v[12:15]
	v_mfma_f32_16x16x32_bf16 v[12:15], v[172:175], v[152:155], v[12:15]
	v_mfma_f32_16x16x32_bf16 v[8:11], v[176:179], v[136:139], v[8:11]
	v_mfma_f32_16x16x32_bf16 v[8:11], v[180:183], v[152:155], v[8:11]
	s_branch .LBB0_368
.LBB0_368:
	s_barrier
	s_add_i32 s72, s72, 2
	s_add_u32 s60, s60, 0x100
	s_addc_u32 s61, s61, 0
	s_cmp_gt_u32 s72, 29
	s_cbranch_scc1 .LBB0_377

.LBB0_557:
	s_mov_b32 s20, s17
	s_mov_b32 s16, s21
	s_ashr_i32 s21, s17, 31
	s_xor_b64 s[62:63], s[26:27], -1
	s_lshl_b64 s[12:13], s[20:21], 18
	s_add_u32 s12, s18, s12
	s_addc_u32 s13, s19, s13
	s_cmp_gt_i32 s33, 0
	s_cselect_b32 s14, 0x20000, 0
	s_add_u32 s42, s12, s14
	s_addc_u32 s43, s13, 0
	s_and_b64 s[12:13], s[24:25], exec
	s_mov_b32 s77, s33
	s_cselect_b32 s21, s43, s61
	s_cselect_b32 s33, s42, s60
	s_ashr_i32 s17, s16, 31
	s_lshl_b64 s[12:13], s[16:17], 18
	s_add_u32 s44, s22, s12
	s_addc_u32 s45, s23, s13
	s_and_b64 s[12:13], s[24:25], exec
	s_cselect_b32 s17, s45, s51
	s_cselect_b32 s35, s44, s50
	s_cmp_gt_i32 s77, -1
	s_cselect_b64 s[48:49], -1, 0
	s_add_u32 s12, s60, 0x80
	v_cndmask_b32_e64 v2, 0, 1, s[48:49]
	v_cndmask_b32_e64 v8, 0, 1, s[26:27]
	s_addc_u32 s13, s61, 0
	v_cndmask_b32_e64 v2, v8, v2, s[24:25]
	v_lshl_add_u64 v[8:9], s[12:13], 0, v[216:217]
	v_and_b32_e32 v2, 1, v2
	v_lshl_add_u64 v[222:223], v[8:9], 0, v[220:221]
	v_lshl_add_u64 v[8:9], s[12:13], 0, v[218:219]
	v_cmp_eq_u32_e32 vcc, 1, v2
	v_mov_b32_e32 v2, 0x20000
	v_lshl_add_u64 v[224:225], v[8:9], 0, v[220:221]
	s_add_u32 s26, s50, 0x100
	v_cndmask_b32_e64 v2, v2, 0, vcc
	s_addc_u32 s27, s51, 0
	s_mov_b32 s57, -2
	s_mov_b64 s[64:65], 0
	v_add_u32_e32 v168, 0x10000, v240
	v_add_u32_e32 v180, 0x14000, v240
	v_lshl_add_u64 v[226:227], v[224:225], 0, s[64:65]
	s_add_i32 m0, s38, 0xc000
	s_waitcnt lgkmcnt(0)
	ds_read_b128 v[148:151], v239
	ds_read_b128 v[164:167], v239 offset:1024
	ds_read_b128 v[144:147], v239 offset:2048
	ds_read_b128 v[160:163], v239 offset:3072
	ds_read_b128 v[140:143], v239 offset:4096
	ds_read_b128 v[156:159], v239 offset:5120
	ds_read_b128 v[136:139], v239 offset:6144
	ds_read_b128 v[152:155], v239 offset:7168
	ds_read_b128 v[184:187], v168
	ds_read_b128 v[188:191], v168 offset:1024
	ds_read_b128 v[192:195], v168 offset:2048
	ds_read_b128 v[196:199], v168 offset:3072
	ds_read_b128 v[168:171], v180
	ds_read_b128 v[172:175], v180 offset:1024
	ds_read_b128 v[176:179], v180 offset:2048
	ds_read_b128 v[180:183], v180 offset:3072
	global_load_lds_dwordx4 v[226:227], off
	v_lshl_add_u64 v[226:227], v[222:223], 0, s[64:65]
	s_add_i32 m0, s38, 0xe000
	s_nop 0
	global_load_lds_dwordx4 v[226:227], off
	s_waitcnt vmcnt(8)
	s_waitcnt lgkmcnt(0)
	s_barrier
	s_waitcnt lgkmcnt(0)
	v_mfma_f32_16x16x32_bf16 v[132:135], v[184:187], v[148:151], 0
	v_mfma_f32_16x16x32_bf16 v[132:135], v[188:191], v[164:167], v[132:135]
	v_mfma_f32_16x16x32_bf16 v[128:131], v[192:195], v[148:151], 0
	v_mfma_f32_16x16x32_bf16 v[128:131], v[196:199], v[164:167], v[128:131]
	v_mfma_f32_16x16x32_bf16 v[124:127], v[168:171], v[148:151], 0
	v_mfma_f32_16x16x32_bf16 v[124:127], v[172:175], v[164:167], v[124:127]
	v_mfma_f32_16x16x32_bf16 v[120:123], v[176:179], v[148:151], 0
	v_mfma_f32_16x16x32_bf16 v[120:123], v[180:183], v[164:167], v[120:123]
	v_mfma_f32_16x16x32_bf16 v[116:119], v[184:187], v[144:147], 0
	v_mfma_f32_16x16x32_bf16 v[116:119], v[188:191], v[160:163], v[116:119]
	v_mfma_f32_16x16x32_bf16 v[112:115], v[192:195], v[144:147], 0
	v_mfma_f32_16x16x32_bf16 v[112:115], v[196:199], v[160:163], v[112:115]
	v_mfma_f32_16x16x32_bf16 v[108:111], v[168:171], v[144:147], 0
	v_mfma_f32_16x16x32_bf16 v[108:111], v[172:175], v[160:163], v[108:111]
	v_mfma_f32_16x16x32_bf16 v[104:107], v[176:179], v[144:147], 0
	v_mfma_f32_16x16x32_bf16 v[104:107], v[180:183], v[160:163], v[104:107]
	v_mfma_f32_16x16x32_bf16 v[100:103], v[184:187], v[140:143], 0
	v_mfma_f32_16x16x32_bf16 v[100:103], v[188:191], v[156:159], v[100:103]
	v_mfma_f32_16x16x32_bf16 v[96:99], v[192:195], v[140:143], 0
	v_mfma_f32_16x16x32_bf16 v[96:99], v[196:199], v[156:159], v[96:99]
	v_mfma_f32_16x16x32_bf16 v[92:95], v[168:171], v[140:143], 0
	v_mfma_f32_16x16x32_bf16 v[92:95], v[172:175], v[156:159], v[92:95]
	v_mfma_f32_16x16x32_bf16 v[88:91], v[176:179], v[140:143], 0
	v_mfma_f32_16x16x32_bf16 v[88:91], v[180:183], v[156:159], v[88:91]
	v_mfma_f32_16x16x32_bf16 v[84:87], v[184:187], v[136:139], 0
	v_mfma_f32_16x16x32_bf16 v[84:87], v[188:191], v[152:155], v[84:87]
	v_mfma_f32_16x16x32_bf16 v[80:83], v[192:195], v[136:139], 0
	v_mfma_f32_16x16x32_bf16 v[80:83], v[196:199], v[152:155], v[80:83]
	v_mfma_f32_16x16x32_bf16 v[76:79], v[168:171], v[136:139], 0
	v_mfma_f32_16x16x32_bf16 v[76:79], v[172:175], v[152:155], v[76:79]
	v_mfma_f32_16x16x32_bf16 v[72:75], v[176:179], v[136:139], 0
	v_mfma_f32_16x16x32_bf16 v[72:75], v[180:183], v[152:155], v[72:75]
	s_barrier
	v_cndmask_b32_e64 v204, 0, 1, s[62:63]
	v_cmp_ne_u32_e64 s[50:51], 1, v204
	s_andn2_b64 vcc, exec, s[62:63]
	s_cbranch_vccnz .Lpeel2_561
	ds_read_b128 v[148:151], v239 offset:16384
	ds_read_b128 v[164:167], v239 offset:17408
	ds_read_b128 v[144:147], v239 offset:18432
	ds_read_b128 v[160:163], v239 offset:19456
	ds_read_b128 v[140:143], v239 offset:20480
	ds_read_b128 v[156:159], v239 offset:21504
	ds_read_b128 v[136:139], v239 offset:22528
	ds_read_b128 v[152:155], v239 offset:23552
.Lpeel2_561:
	s_add_u32 s12, s60, s64
	s_addc_u32 s13, s61, s65
	s_add_u32 s14, s12, 0x100
	s_addc_u32 s15, s13, 0
	s_add_u32 s79, s26, s64
	s_addc_u32 s80, s27, s65
	s_cmpk_eq_i32 s64, 0x300
	s_cselect_b64 s[52:53], -1, 0
	s_and_b64 s[12:13], s[52:53], exec
	s_cselect_b32 s13, s17, s80
	s_cselect_b32 s12, s35, s79
	s_mov_b32 m0, s39
	s_cselect_b32 s15, s21, s15
	s_cselect_b32 s14, s33, s14
	v_lshl_add_u64 v[226:227], s[12:13], 0, v[4:5]
	s_add_u32 s80, s12, 0x20000
	global_load_lds_dwordx4 v[226:227], off
	v_lshl_add_u64 v[228:229], s[12:13], 0, v[208:209]
	s_mov_b32 m0, s40
	s_addc_u32 s81, s13, 0
	global_load_lds_dwordx4 v[228:229], off
	v_lshl_add_u64 v[230:231], s[80:81], 0, v[4:5]
	s_mov_b32 m0, s41
	v_lshl_add_u64 v[232:233], s[14:15], 0, v[208:209]
	global_load_lds_dwordx4 v[230:231], off
	v_lshl_add_u64 v[230:231], s[80:81], 0, v[208:209]
	s_mov_b32 m0, s47
	s_and_b64 vcc, exec, s[50:51]
	global_load_lds_dwordx4 v[230:231], off
	v_lshl_add_u64 v[230:231], s[14:15], 0, v[4:5]
	s_mov_b32 m0, s38
	s_nop 0
	global_load_lds_dwordx4 v[230:231], off
	s_mov_b32 m0, s59
	s_nop 0
	global_load_lds_dwordx4 v[232:233], off
	s_waitcnt vmcnt(8)
	s_waitcnt lgkmcnt(0)
	s_barrier
	s_cbranch_vccnz .Lpeel2_563
	s_waitcnt lgkmcnt(0)
	v_mfma_f32_16x16x32_bf16 v[68:71], v[184:187], v[148:151], 0
	v_mfma_f32_16x16x32_bf16 v[68:71], v[188:191], v[164:167], v[68:71]
	v_mfma_f32_16x16x32_bf16 v[64:67], v[192:195], v[148:151], 0
	v_mfma_f32_16x16x32_bf16 v[64:67], v[196:199], v[164:167], v[64:67]
	v_mfma_f32_16x16x32_bf16 v[60:63], v[168:171], v[148:151], 0
	v_mfma_f32_16x16x32_bf16 v[60:63], v[172:175], v[164:167], v[60:63]
	v_mfma_f32_16x16x32_bf16 v[56:59], v[176:179], v[148:151], 0
	v_mfma_f32_16x16x32_bf16 v[56:59], v[180:183], v[164:167], v[56:59]
	v_mfma_f32_16x16x32_bf16 v[52:55], v[184:187], v[144:147], 0
	v_mfma_f32_16x16x32_bf16 v[52:55], v[188:191], v[160:163], v[52:55]
	v_mfma_f32_16x16x32_bf16 v[48:51], v[192:195], v[144:147], 0
	v_mfma_f32_16x16x32_bf16 v[48:51], v[196:199], v[160:163], v[48:51]
	v_mfma_f32_16x16x32_bf16 v[44:47], v[168:171], v[144:147], 0
	v_mfma_f32_16x16x32_bf16 v[44:47], v[172:175], v[160:163], v[44:47]
	v_mfma_f32_16x16x32_bf16 v[40:43], v[176:179], v[144:147], 0
	v_mfma_f32_16x16x32_bf16 v[40:43], v[180:183], v[160:163], v[40:43]
	v_mfma_f32_16x16x32_bf16 v[36:39], v[184:187], v[140:143], 0
	v_mfma_f32_16x16x32_bf16 v[36:39], v[188:191], v[156:159], v[36:39]
	v_mfma_f32_16x16x32_bf16 v[32:35], v[192:195], v[140:143], 0
	v_mfma_f32_16x16x32_bf16 v[32:35], v[196:199], v[156:159], v[32:35]
	v_mfma_f32_16x16x32_bf16 v[28:31], v[168:171], v[140:143], 0
	v_mfma_f32_16x16x32_bf16 v[28:31], v[172:175], v[156:159], v[28:31]
	v_mfma_f32_16x16x32_bf16 v[24:27], v[176:179], v[140:143], 0
	v_mfma_f32_16x16x32_bf16 v[24:27], v[180:183], v[156:159], v[24:27]
	v_mfma_f32_16x16x32_bf16 v[20:23], v[184:187], v[136:139], 0
	v_mfma_f32_16x16x32_bf16 v[20:23], v[188:191], v[152:155], v[20:23]
	v_mfma_f32_16x16x32_bf16 v[16:19], v[192:195], v[136:139], 0
	v_mfma_f32_16x16x32_bf16 v[16:19], v[196:199], v[152:155], v[16:19]
	v_mfma_f32_16x16x32_bf16 v[12:15], v[168:171], v[136:139], 0
	v_mfma_f32_16x16x32_bf16 v[12:15], v[172:175], v[152:155], v[12:15]
	v_mfma_f32_16x16x32_bf16 v[8:11], v[176:179], v[136:139], 0
	v_mfma_f32_16x16x32_bf16 v[8:11], v[180:183], v[152:155], v[8:11]

.Lpeel2_565:
	s_mov_b32 m0, s70
	v_lshl_add_u64 v[204:205], v[226:227], 0, s[0:1]
	s_add_u32 s12, s12, 0x20080
	global_load_lds_dwordx4 v[204:205], off
	v_lshl_add_u64 v[204:205], v[228:229], 0, s[0:1]
	s_mov_b32 m0, s71
	s_addc_u32 s13, s13, 0
	global_load_lds_dwordx4 v[204:205], off
	v_lshl_add_u64 v[204:205], s[12:13], 0, v[4:5]
	s_mov_b32 m0, s74
	s_and_b64 vcc, exec, s[50:51]
	global_load_lds_dwordx4 v[204:205], off
	v_lshl_add_u64 v[204:205], s[12:13], 0, v[208:209]
	s_mov_b32 m0, s75
	s_nop 0
	global_load_lds_dwordx4 v[204:205], off
	v_lshl_add_u64 v[204:205], v[230:231], 0, s[0:1]
	s_mov_b32 m0, s72
	s_nop 0
	global_load_lds_dwordx4 v[204:205], off
	v_lshl_add_u64 v[204:205], v[232:233], 0, s[0:1]
	s_mov_b32 m0, s73
	s_nop 0
	global_load_lds_dwordx4 v[204:205], off
	s_waitcnt vmcnt(8)
	s_waitcnt lgkmcnt(0)
	s_barrier
	s_cbranch_vccnz .LBB0_558
	s_waitcnt lgkmcnt(0)
	v_mfma_f32_16x16x32_bf16 v[68:71], v[184:187], v[148:151], v[68:71]
	v_mfma_f32_16x16x32_bf16 v[68:71], v[188:191], v[164:167], v[68:71]
	v_mfma_f32_16x16x32_bf16 v[64:67], v[192:195], v[148:151], v[64:67]
	v_mfma_f32_16x16x32_bf16 v[64:67], v[196:199], v[164:167], v[64:67]
	v_mfma_f32_16x16x32_bf16 v[60:63], v[168:171], v[148:151], v[60:63]
	v_mfma_f32_16x16x32_bf16 v[60:63], v[172:175], v[164:167], v[60:63]
	v_mfma_f32_16x16x32_bf16 v[56:59], v[176:179], v[148:151], v[56:59]
	v_mfma_f32_16x16x32_bf16 v[56:59], v[180:183], v[164:167], v[56:59]
	v_mfma_f32_16x16x32_bf16 v[52:55], v[184:187], v[144:147], v[52:55]
	v_mfma_f32_16x16x32_bf16 v[52:55], v[188:191], v[160:163], v[52:55]
	v_mfma_f32_16x16x32_bf16 v[48:51], v[192:195], v[144:147], v[48:51]
	v_mfma_f32_16x16x32_bf16 v[48:51], v[196:199], v[160:163], v[48:51]
	v_mfma_f32_16x16x32_bf16 v[44:47], v[168:171], v[144:147], v[44:47]
	v_mfma_f32_16x16x32_bf16 v[44:47], v[172:175], v[160:163], v[44:47]
	v_mfma_f32_16x16x32_bf16 v[40:43], v[176:179], v[144:147], v[40:43]
	v_mfma_f32_16x16x32_bf16 v[40:43], v[180:183], v[160:163], v[40:43]
	v_mfma_f32_16x16x32_bf16 v[36:39], v[184:187], v[140:143], v[36:39]
	v_mfma_f32_16x16x32_bf16 v[36:39], v[188:191], v[156:159], v[36:39]
	v_mfma_f32_16x16x32_bf16 v[32:35], v[192:195], v[140:143], v[32:35]
	v_mfma_f32_16x16x32_bf16 v[32:35], v[196:199], v[156:159], v[32:35]
	v_mfma_f32_16x16x32_bf16 v[28:31], v[168:171], v[140:143], v[28:31]
	v_mfma_f32_16x16x32_bf16 v[28:31], v[172:175], v[156:159], v[28:31]
	v_mfma_f32_16x16x32_bf16 v[24:27], v[176:179], v[140:143], v[24:27]
	v_mfma_f32_16x16x32_bf16 v[24:27], v[180:183], v[156:159], v[24:27]
	v_mfma_f32_16x16x32_bf16 v[20:23], v[184:187], v[136:139], v[20:23]
	v_mfma_f32_16x16x32_bf16 v[20:23], v[188:191], v[152:155], v[20:23]
	v_mfma_f32_16x16x32_bf16 v[16:19], v[192:195], v[136:139], v[16:19]
	v_mfma_f32_16x16x32_bf16 v[16:19], v[196:199], v[152:155], v[16:19]
	v_mfma_f32_16x16x32_bf16 v[12:15], v[168:171], v[136:139], v[12:15]
	v_mfma_f32_16x16x32_bf16 v[12:15], v[172:175], v[152:155], v[12:15]
	v_mfma_f32_16x16x32_bf16 v[8:11], v[176:179], v[136:139], v[8:11]
	v_mfma_f32_16x16x32_bf16 v[8:11], v[180:183], v[152:155], v[8:11]
	s_branch .LBB0_558
.LBB0_558:
	s_barrier
	s_add_i32 s57, s57, 2
	s_add_u32 s64, s64, 0x100
	s_addc_u32 s65, s65, 0
	s_cmp_gt_u32 s57, 5
	s_cbranch_scc1 .LBB0_567

.LBB0_619:
	s_ashr_i32 s17, s16, 31
	s_lshl_b64 s[14:15], s[16:17], 18
	s_add_u32 s20, s18, s14
	s_addc_u32 s21, s19, s15
	s_and_b64 s[14:15], s[50:51], exec
	s_cselect_b32 s17, s21, s13
	s_cselect_b32 s33, s20, s12
	s_ashr_i32 s11, s10, 31
	s_lshl_b64 s[14:15], s[10:11], 18
	s_add_u32 s24, s22, s14
	s_addc_u32 s25, s23, s15
	s_and_b64 s[14:15], s[50:51], exec
	s_cselect_b32 s11, s25, s27
	s_cselect_b32 s37, s24, s26
	s_add_u32 s42, s12, 0x20080
	s_addc_u32 s43, s13, 0
	s_add_u32 s26, s26, 0x100
	v_mov_b32_e32 v8, 0
	s_addc_u32 s27, s27, 0
	s_mov_b32 s57, -2
	s_add_u32 s12, s42, 0xfffe0080
	s_addc_u32 s13, s43, -1
	s_cmp_eq_u32 s57, 4
	s_cselect_b32 s15, s17, s13
	s_cselect_b32 s14, s33, s12
	s_cselect_b32 s13, s11, s27
	s_cselect_b32 s12, s37, s26
	s_add_i32 s58, 0, 0x10000
	v_add_u32_e32 v136, s58, v1
	s_add_i32 s60, 0, 0x14000
	ds_read_b128 v[150:153], v7
	ds_read_b128 v[154:157], v7 offset:1024
	ds_read_b128 v[158:161], v7 offset:2048
	ds_read_b128 v[162:165], v7 offset:3072
	ds_read_b128 v[166:169], v7 offset:4096
	ds_read_b128 v[170:173], v7 offset:5120
	ds_read_b128 v[174:177], v7 offset:6144
	ds_read_b128 v[178:181], v7 offset:7168
	ds_read_b128 v[182:185], v136
	ds_read_b128 v[186:189], v136 offset:1024
	ds_read_b128 v[190:193], v136 offset:2048
	ds_read_b128 v[194:197], v136 offset:3072
	v_add_u32_e32 v136, s60, v1
	ds_read_b128 v[208:211], v136
	ds_read_b128 v[212:215], v136 offset:1024
	ds_read_b128 v[216:219], v136 offset:2048
	ds_read_b128 v[220:223], v136 offset:3072
	v_lshl_add_u64 v[136:137], s[42:43], 0, v[146:147]
	s_add_i32 m0, s38, 0xc000
	s_nop 0
	global_load_lds_dwordx4 v[136:137], off
	v_lshl_add_u64 v[136:137], s[42:43], 0, v[148:149]
	s_add_i32 m0, s38, 0xe000
	s_nop 0
	global_load_lds_dwordx4 v[136:137], off
	s_waitcnt vmcnt(8)
	s_waitcnt lgkmcnt(0)
	s_barrier
	s_waitcnt lgkmcnt(0)
	v_mfma_f32_16x16x32_bf16 v[132:135], v[182:185], v[150:153], 0
	v_mfma_f32_16x16x32_bf16 v[132:135], v[186:189], v[154:157], v[132:135]
	v_mfma_f32_16x16x32_bf16 v[128:131], v[190:193], v[150:153], 0
	v_mfma_f32_16x16x32_bf16 v[128:131], v[194:197], v[154:157], v[128:131]
	v_mfma_f32_16x16x32_bf16 v[112:115], v[208:211], v[150:153], 0
	v_mfma_f32_16x16x32_bf16 v[112:115], v[212:215], v[154:157], v[112:115]
	v_mfma_f32_16x16x32_bf16 v[104:107], v[216:219], v[150:153], 0
	v_mfma_f32_16x16x32_bf16 v[104:107], v[220:223], v[154:157], v[104:107]
	v_mfma_f32_16x16x32_bf16 v[124:127], v[182:185], v[158:161], 0
	v_mfma_f32_16x16x32_bf16 v[124:127], v[186:189], v[162:165], v[124:127]
	v_mfma_f32_16x16x32_bf16 v[120:123], v[190:193], v[158:161], 0
	v_mfma_f32_16x16x32_bf16 v[120:123], v[194:197], v[162:165], v[120:123]
	v_mfma_f32_16x16x32_bf16 v[96:99], v[208:211], v[158:161], 0
	v_mfma_f32_16x16x32_bf16 v[96:99], v[212:215], v[162:165], v[96:99]
	v_mfma_f32_16x16x32_bf16 v[88:91], v[216:219], v[158:161], 0
	v_mfma_f32_16x16x32_bf16 v[88:91], v[220:223], v[162:165], v[88:91]
	v_mfma_f32_16x16x32_bf16 v[116:119], v[182:185], v[166:169], 0
	v_mfma_f32_16x16x32_bf16 v[116:119], v[186:189], v[170:173], v[116:119]
	v_mfma_f32_16x16x32_bf16 v[108:111], v[190:193], v[166:169], 0
	v_mfma_f32_16x16x32_bf16 v[108:111], v[194:197], v[170:173], v[108:111]
	v_mfma_f32_16x16x32_bf16 v[84:87], v[208:211], v[166:169], 0
	v_mfma_f32_16x16x32_bf16 v[84:87], v[212:215], v[170:173], v[84:87]
	v_mfma_f32_16x16x32_bf16 v[80:83], v[216:219], v[166:169], 0
	v_mfma_f32_16x16x32_bf16 v[80:83], v[220:223], v[170:173], v[80:83]
	v_mfma_f32_16x16x32_bf16 v[100:103], v[182:185], v[174:177], 0
	v_mfma_f32_16x16x32_bf16 v[100:103], v[186:189], v[178:181], v[100:103]
	v_mfma_f32_16x16x32_bf16 v[92:95], v[190:193], v[174:177], 0
	v_mfma_f32_16x16x32_bf16 v[92:95], v[194:197], v[178:181], v[92:95]
	v_mfma_f32_16x16x32_bf16 v[76:79], v[208:211], v[174:177], 0
	v_mfma_f32_16x16x32_bf16 v[76:79], v[212:215], v[178:181], v[76:79]
	v_mfma_f32_16x16x32_bf16 v[72:75], v[216:219], v[174:177], 0
	v_mfma_f32_16x16x32_bf16 v[72:75], v[220:223], v[178:181], v[72:75]
	s_barrier
	s_add_i32 s58, s58, s35
	v_lshl_add_u64 v[136:137], s[12:13], 0, v[2:3]
	s_mov_b32 m0, s58
	ds_read_b128 v[150:153], v7 offset:16384
	ds_read_b128 v[154:157], v7 offset:17408
	ds_read_b128 v[158:161], v7 offset:18432
	ds_read_b128 v[162:165], v7 offset:19456
	ds_read_b128 v[166:169], v7 offset:20480
	ds_read_b128 v[170:173], v7 offset:21504
	ds_read_b128 v[174:177], v7 offset:22528
	ds_read_b128 v[178:181], v7 offset:23552
	global_load_lds_dwordx4 v[136:137], off
	s_add_i32 m0, s58, 0x2000
	s_add_u32 s58, s12, 0x20000
	v_lshl_add_u64 v[198:199], s[12:13], 0, v[4:5]
	s_addc_u32 s59, s13, 0
	s_add_i32 s60, s60, s35
	global_load_lds_dwordx4 v[198:199], off
	v_lshl_add_u64 v[204:205], s[58:59], 0, v[2:3]
	s_mov_b32 m0, s60
	v_lshl_add_u64 v[224:225], s[14:15], 0, v[138:139]
	global_load_lds_dwordx4 v[204:205], off
	v_lshl_add_u64 v[204:205], s[58:59], 0, v[4:5]
	s_add_i32 m0, s60, 0x2000
	s_nop 0
	global_load_lds_dwordx4 v[204:205], off
	v_lshl_add_u64 v[204:205], s[14:15], 0, v[140:141]
	s_mov_b32 m0, s38
	s_nop 0
	global_load_lds_dwordx4 v[204:205], off
	s_mov_b32 m0, s39
	s_nop 0
	global_load_lds_dwordx4 v[224:225], off
	s_waitcnt vmcnt(8)
	s_waitcnt lgkmcnt(0)
	s_barrier
	s_waitcnt lgkmcnt(0)
	v_mfma_f32_16x16x32_bf16 v[68:71], v[182:185], v[150:153], 0
	v_mfma_f32_16x16x32_bf16 v[68:71], v[186:189], v[154:157], v[68:71]
	v_mfma_f32_16x16x32_bf16 v[64:67], v[190:193], v[150:153], 0
	v_mfma_f32_16x16x32_bf16 v[64:67], v[194:197], v[154:157], v[64:67]
	v_mfma_f32_16x16x32_bf16 v[48:51], v[208:211], v[150:153], 0
	v_mfma_f32_16x16x32_bf16 v[48:51], v[212:215], v[154:157], v[48:51]
	v_mfma_f32_16x16x32_bf16 v[40:43], v[216:219], v[150:153], 0
	v_mfma_f32_16x16x32_bf16 v[40:43], v[220:223], v[154:157], v[40:43]
	v_mfma_f32_16x16x32_bf16 v[60:63], v[182:185], v[158:161], 0
	v_mfma_f32_16x16x32_bf16 v[60:63], v[186:189], v[162:165], v[60:63]
	v_mfma_f32_16x16x32_bf16 v[56:59], v[190:193], v[158:161], 0
	v_mfma_f32_16x16x32_bf16 v[56:59], v[194:197], v[162:165], v[56:59]
	v_mfma_f32_16x16x32_bf16 v[32:35], v[208:211], v[158:161], 0
	v_mfma_f32_16x16x32_bf16 v[32:35], v[212:215], v[162:165], v[32:35]
	v_mfma_f32_16x16x32_bf16 v[24:27], v[216:219], v[158:161], 0
	v_mfma_f32_16x16x32_bf16 v[24:27], v[220:223], v[162:165], v[24:27]
	v_mfma_f32_16x16x32_bf16 v[52:55], v[182:185], v[166:169], 0
	v_mfma_f32_16x16x32_bf16 v[52:55], v[186:189], v[170:173], v[52:55]
	v_mfma_f32_16x16x32_bf16 v[44:47], v[190:193], v[166:169], 0
	v_mfma_f32_16x16x32_bf16 v[44:47], v[194:197], v[170:173], v[44:47]
	v_mfma_f32_16x16x32_bf16 v[20:23], v[208:211], v[166:169], 0
	v_mfma_f32_16x16x32_bf16 v[20:23], v[212:215], v[170:173], v[20:23]
	v_mfma_f32_16x16x32_bf16 v[16:19], v[216:219], v[166:169], 0
	v_mfma_f32_16x16x32_bf16 v[16:19], v[220:223], v[170:173], v[16:19]
	v_mfma_f32_16x16x32_bf16 v[36:39], v[182:185], v[174:177], 0
	v_mfma_f32_16x16x32_bf16 v[36:39], v[186:189], v[178:181], v[36:39]
	v_mfma_f32_16x16x32_bf16 v[28:31], v[190:193], v[174:177], 0
	v_mfma_f32_16x16x32_bf16 v[28:31], v[194:197], v[178:181], v[28:31]
	v_mfma_f32_16x16x32_bf16 v[12:15], v[208:211], v[174:177], 0
	v_mfma_f32_16x16x32_bf16 v[12:15], v[212:215], v[178:181], v[12:15]
	v_mfma_f32_16x16x32_bf16 v[8:11], v[216:219], v[174:177], 0
	v_mfma_f32_16x16x32_bf16 v[8:11], v[220:223], v[178:181], v[8:11]
	s_barrier
	s_add_i32 s58, 0, 0x18000
	s_add_i32 s59, 0, 0x1c000
	s_add_u32 s14, s14, 0x20000
	s_addc_u32 s15, s15, 0
	s_mov_b32 m0, s40
	v_add_u32_e32 v194, s58, v1
	v_add_u32_e32 v207, s59, v1
	v_lshl_add_u64 v[226:227], s[14:15], 0, v[140:141]
	ds_read_b128 v[150:153], v7 offset:32768
	ds_read_b128 v[154:157], v7 offset:33792
	ds_read_b128 v[158:161], v7 offset:34816
	ds_read_b128 v[162:165], v7 offset:35840
	ds_read_b128 v[166:169], v7 offset:36864
	ds_read_b128 v[170:173], v7 offset:37888
	ds_read_b128 v[174:177], v7 offset:38912
	ds_read_b128 v[178:181], v7 offset:39936
	ds_read_b128 v[182:185], v194
	ds_read_b128 v[186:189], v194 offset:1024
	ds_read_b128 v[190:193], v194 offset:2048
	ds_read_b128 v[194:197], v194 offset:3072
	ds_read_b128 v[208:211], v207
	ds_read_b128 v[212:215], v207 offset:1024
	ds_read_b128 v[216:219], v207 offset:2048
	ds_read_b128 v[220:223], v207 offset:3072
	global_load_lds_dwordx4 v[226:227], off
	v_lshl_add_u64 v[226:227], s[14:15], 0, v[138:139]
	s_mov_b32 m0, s41
	s_nop 0
	global_load_lds_dwordx4 v[226:227], off
	s_waitcnt vmcnt(8)
	s_waitcnt lgkmcnt(0)
	s_barrier
	s_waitcnt lgkmcnt(0)
	v_mfma_f32_16x16x32_bf16 v[132:135], v[182:185], v[150:153], v[132:135]
	v_mfma_f32_16x16x32_bf16 v[132:135], v[186:189], v[154:157], v[132:135]
	v_mfma_f32_16x16x32_bf16 v[128:131], v[190:193], v[150:153], v[128:131]
	v_mfma_f32_16x16x32_bf16 v[128:131], v[194:197], v[154:157], v[128:131]
	v_mfma_f32_16x16x32_bf16 v[112:115], v[208:211], v[150:153], v[112:115]
	v_mfma_f32_16x16x32_bf16 v[112:115], v[212:215], v[154:157], v[112:115]
	v_mfma_f32_16x16x32_bf16 v[104:107], v[216:219], v[150:153], v[104:107]
	v_mfma_f32_16x16x32_bf16 v[104:107], v[220:223], v[154:157], v[104:107]
	v_mfma_f32_16x16x32_bf16 v[124:127], v[182:185], v[158:161], v[124:127]
	v_mfma_f32_16x16x32_bf16 v[124:127], v[186:189], v[162:165], v[124:127]
	v_mfma_f32_16x16x32_bf16 v[120:123], v[190:193], v[158:161], v[120:123]
	v_mfma_f32_16x16x32_bf16 v[120:123], v[194:197], v[162:165], v[120:123]
	v_mfma_f32_16x16x32_bf16 v[96:99], v[208:211], v[158:161], v[96:99]
	v_mfma_f32_16x16x32_bf16 v[96:99], v[212:215], v[162:165], v[96:99]
	v_mfma_f32_16x16x32_bf16 v[88:91], v[216:219], v[158:161], v[88:91]
	v_mfma_f32_16x16x32_bf16 v[88:91], v[220:223], v[162:165], v[88:91]
	v_mfma_f32_16x16x32_bf16 v[116:119], v[182:185], v[166:169], v[116:119]
	v_mfma_f32_16x16x32_bf16 v[116:119], v[186:189], v[170:173], v[116:119]
	v_mfma_f32_16x16x32_bf16 v[108:111], v[190:193], v[166:169], v[108:111]
	v_mfma_f32_16x16x32_bf16 v[108:111], v[194:197], v[170:173], v[108:111]
	v_mfma_f32_16x16x32_bf16 v[84:87], v[208:211], v[166:169], v[84:87]
	v_mfma_f32_16x16x32_bf16 v[84:87], v[212:215], v[170:173], v[84:87]
	v_mfma_f32_16x16x32_bf16 v[80:83], v[216:219], v[166:169], v[80:83]
	v_mfma_f32_16x16x32_bf16 v[80:83], v[220:223], v[170:173], v[80:83]
	v_mfma_f32_16x16x32_bf16 v[100:103], v[182:185], v[174:177], v[100:103]
	v_mfma_f32_16x16x32_bf16 v[100:103], v[186:189], v[178:181], v[100:103]
	v_mfma_f32_16x16x32_bf16 v[92:95], v[190:193], v[174:177], v[92:95]
	v_mfma_f32_16x16x32_bf16 v[92:95], v[194:197], v[178:181], v[92:95]
	v_mfma_f32_16x16x32_bf16 v[76:79], v[208:211], v[174:177], v[76:79]
	v_mfma_f32_16x16x32_bf16 v[76:79], v[212:215], v[178:181], v[76:79]
	v_mfma_f32_16x16x32_bf16 v[72:75], v[216:219], v[174:177], v[72:75]
	v_mfma_f32_16x16x32_bf16 v[72:75], v[220:223], v[178:181], v[72:75]
	s_barrier
	s_add_i32 s14, s58, s35
	v_lshl_add_u64 v[136:137], v[136:137], 0, s[0:1]
	s_mov_b32 m0, s14
	ds_read_b128 v[150:153], v7 offset:49152
	ds_read_b128 v[154:157], v7 offset:50176
	ds_read_b128 v[158:161], v7 offset:51200
	ds_read_b128 v[162:165], v7 offset:52224
	ds_read_b128 v[166:169], v7 offset:53248
	ds_read_b128 v[170:173], v7 offset:54272
	ds_read_b128 v[174:177], v7 offset:55296
	ds_read_b128 v[178:181], v7 offset:56320
	global_load_lds_dwordx4 v[136:137], off
	s_add_i32 m0, s14, 0x2000
	s_add_u32 s12, s12, 0x20080
	v_lshl_add_u64 v[136:137], v[198:199], 0, s[0:1]
	s_addc_u32 s13, s13, 0
	s_add_i32 s14, s59, s35
	global_load_lds_dwordx4 v[136:137], off
	v_lshl_add_u64 v[136:137], s[12:13], 0, v[2:3]
	s_mov_b32 m0, s14
	s_nop 0
	global_load_lds_dwordx4 v[136:137], off
	v_lshl_add_u64 v[136:137], s[12:13], 0, v[4:5]
	s_add_i32 m0, s14, 0x2000
	s_nop 0
	global_load_lds_dwordx4 v[136:137], off
	v_lshl_add_u64 v[136:137], v[204:205], 0, s[0:1]
	s_mov_b32 m0, s49
	s_nop 0
	global_load_lds_dwordx4 v[136:137], off
	v_lshl_add_u64 v[136:137], v[224:225], 0, s[0:1]
	s_mov_b32 m0, s52
	s_nop 0
	global_load_lds_dwordx4 v[136:137], off
	s_waitcnt vmcnt(8)
	s_waitcnt lgkmcnt(0)
	s_barrier
	s_waitcnt lgkmcnt(0)
	v_mfma_f32_16x16x32_bf16 v[68:71], v[182:185], v[150:153], v[68:71]
	v_mfma_f32_16x16x32_bf16 v[68:71], v[186:189], v[154:157], v[68:71]
	v_mfma_f32_16x16x32_bf16 v[64:67], v[190:193], v[150:153], v[64:67]
	v_mfma_f32_16x16x32_bf16 v[64:67], v[194:197], v[154:157], v[64:67]
	v_mfma_f32_16x16x32_bf16 v[48:51], v[208:211], v[150:153], v[48:51]
	v_mfma_f32_16x16x32_bf16 v[48:51], v[212:215], v[154:157], v[48:51]
	v_mfma_f32_16x16x32_bf16 v[40:43], v[216:219], v[150:153], v[40:43]
	v_mfma_f32_16x16x32_bf16 v[40:43], v[220:223], v[154:157], v[40:43]
	v_mfma_f32_16x16x32_bf16 v[60:63], v[182:185], v[158:161], v[60:63]
	v_mfma_f32_16x16x32_bf16 v[60:63], v[186:189], v[162:165], v[60:63]
	v_mfma_f32_16x16x32_bf16 v[56:59], v[190:193], v[158:161], v[56:59]
	v_mfma_f32_16x16x32_bf16 v[56:59], v[194:197], v[162:165], v[56:59]
	v_mfma_f32_16x16x32_bf16 v[32:35], v[208:211], v[158:161], v[32:35]
	v_mfma_f32_16x16x32_bf16 v[32:35], v[212:215], v[162:165], v[32:35]
	v_mfma_f32_16x16x32_bf16 v[24:27], v[216:219], v[158:161], v[24:27]
	v_mfma_f32_16x16x32_bf16 v[24:27], v[220:223], v[162:165], v[24:27]
	v_mfma_f32_16x16x32_bf16 v[52:55], v[182:185], v[166:169], v[52:55]
	v_mfma_f32_16x16x32_bf16 v[52:55], v[186:189], v[170:173], v[52:55]
	v_mfma_f32_16x16x32_bf16 v[44:47], v[190:193], v[166:169], v[44:47]
	v_mfma_f32_16x16x32_bf16 v[44:47], v[194:197], v[170:173], v[44:47]
	v_mfma_f32_16x16x32_bf16 v[20:23], v[208:211], v[166:169], v[20:23]
	v_mfma_f32_16x16x32_bf16 v[20:23], v[212:215], v[170:173], v[20:23]
	v_mfma_f32_16x16x32_bf16 v[16:19], v[216:219], v[166:169], v[16:19]
	v_mfma_f32_16x16x32_bf16 v[16:19], v[220:223], v[170:173], v[16:19]
	v_mfma_f32_16x16x32_bf16 v[36:39], v[182:185], v[174:177], v[36:39]
	v_mfma_f32_16x16x32_bf16 v[36:39], v[186:189], v[178:181], v[36:39]
	v_mfma_f32_16x16x32_bf16 v[28:31], v[190:193], v[174:177], v[28:31]
	v_mfma_f32_16x16x32_bf16 v[28:31], v[194:197], v[178:181], v[28:31]
	v_mfma_f32_16x16x32_bf16 v[12:15], v[208:211], v[174:177], v[12:15]
	v_mfma_f32_16x16x32_bf16 v[12:15], v[212:215], v[178:181], v[12:15]
	v_mfma_f32_16x16x32_bf16 v[8:11], v[216:219], v[174:177], v[8:11]
	v_mfma_f32_16x16x32_bf16 v[8:11], v[220:223], v[178:181], v[8:11]
	s_barrier
	s_add_i32 s57, s57, 2
	s_add_u32 s42, s42, 0x100
	s_addc_u32 s43, s43, 0
	s_add_u32 s26, s26, 0x100
	s_addc_u32 s27, s27, 0
	s_cmp_gt_u32 s57, 5
	s_cbranch_scc0 .LBB0_620
	s_branch .Lpeelb0_exit

.Lpeelb0_exit:
	s_and_b64 vcc, exec, s[6:7]
	s_cbranch_vccz .LBB0_623
	s_barrier

.LBB0_985:
	s_ashr_i32 s21, s20, 31
	s_lshl_b64 s[18:19], s[20:21], 20
	s_add_u32 s24, s22, s18
	s_addc_u32 s25, s23, s19
	s_and_b64 s[18:19], s[48:49], exec
	s_cselect_b32 s18, s25, s15
	s_cselect_b32 s19, s24, s14
	s_ashr_i32 s17, s16, 31
	s_lshl_b64 s[36:37], s[16:17], 20
	s_add_u32 s36, s26, s36
	s_addc_u32 s37, s27, s37
	s_and_b64 s[44:45], s[48:49], exec
	s_cselect_b32 s17, s37, s13
	s_cselect_b32 s21, s36, s12
	s_add_u32 s44, s14, 0x80080
	s_addc_u32 s45, s15, 0
	s_add_u32 s33, s12, 0x100
	v_mov_b32_e32 v8, 0
	s_addc_u32 s43, s13, 0
	s_mov_b32 s50, -2
	s_add_u32 s12, s44, 0xfff80080
	s_addc_u32 s13, s45, -1
	s_cmp_eq_u32 s50, 28
	s_cselect_b32 s15, s18, s13
	s_cselect_b32 s14, s19, s12
	s_cselect_b32 s13, s17, s43
	s_cselect_b32 s12, s21, s33
	s_add_i32 s51, 0, 0x10000
	v_add_u32_e32 v2, s51, v7
	s_add_i32 s63, 0, 0x14000
	ds_read_b128 v[150:153], v155
	ds_read_b128 v[156:159], v155 offset:1024
	ds_read_b128 v[160:163], v155 offset:2048
	ds_read_b128 v[164:167], v155 offset:3072
	ds_read_b128 v[168:171], v155 offset:4096
	ds_read_b128 v[172:175], v155 offset:5120
	ds_read_b128 v[176:179], v155 offset:6144
	ds_read_b128 v[180:183], v155 offset:7168
	ds_read_b128 v[184:187], v2
	ds_read_b128 v[188:191], v2 offset:1024
	ds_read_b128 v[192:195], v2 offset:2048
	ds_read_b128 v[196:199], v2 offset:3072
	v_add_u32_e32 v2, s63, v7
	v_lshl_add_u64 v[224:225], s[44:45], 0, v[146:147]
	s_add_i32 m0, s39, 0xc000
	ds_read_b128 v[208:211], v2
	ds_read_b128 v[212:215], v2 offset:1024
	ds_read_b128 v[216:219], v2 offset:2048
	ds_read_b128 v[220:223], v2 offset:3072
	global_load_lds_dwordx4 v[224:225], off
	v_lshl_add_u64 v[224:225], s[44:45], 0, v[148:149]
	s_add_i32 m0, s39, 0xe000
	s_nop 0
	global_load_lds_dwordx4 v[224:225], off
	s_waitcnt vmcnt(8)
	s_waitcnt lgkmcnt(0)
	s_barrier
	s_waitcnt lgkmcnt(0)
	v_mfma_f32_16x16x32_bf16 v[132:135], v[184:187], v[150:153], 0
	v_mfma_f32_16x16x32_bf16 v[132:135], v[188:191], v[156:159], v[132:135]
	v_mfma_f32_16x16x32_bf16 v[128:131], v[192:195], v[150:153], 0
	v_mfma_f32_16x16x32_bf16 v[128:131], v[196:199], v[156:159], v[128:131]
	v_mfma_f32_16x16x32_bf16 v[124:127], v[208:211], v[150:153], 0
	v_mfma_f32_16x16x32_bf16 v[124:127], v[212:215], v[156:159], v[124:127]
	v_mfma_f32_16x16x32_bf16 v[120:123], v[216:219], v[150:153], 0
	v_mfma_f32_16x16x32_bf16 v[120:123], v[220:223], v[156:159], v[120:123]
	v_mfma_f32_16x16x32_bf16 v[116:119], v[184:187], v[160:163], 0
	v_mfma_f32_16x16x32_bf16 v[116:119], v[188:191], v[164:167], v[116:119]
	v_mfma_f32_16x16x32_bf16 v[112:115], v[192:195], v[160:163], 0
	v_mfma_f32_16x16x32_bf16 v[112:115], v[196:199], v[164:167], v[112:115]
	v_mfma_f32_16x16x32_bf16 v[108:111], v[208:211], v[160:163], 0
	v_mfma_f32_16x16x32_bf16 v[108:111], v[212:215], v[164:167], v[108:111]
	v_mfma_f32_16x16x32_bf16 v[104:107], v[216:219], v[160:163], 0
	v_mfma_f32_16x16x32_bf16 v[104:107], v[220:223], v[164:167], v[104:107]
	v_mfma_f32_16x16x32_bf16 v[100:103], v[184:187], v[168:171], 0
	v_mfma_f32_16x16x32_bf16 v[100:103], v[188:191], v[172:175], v[100:103]
	v_mfma_f32_16x16x32_bf16 v[96:99], v[192:195], v[168:171], 0
	v_mfma_f32_16x16x32_bf16 v[96:99], v[196:199], v[172:175], v[96:99]
	v_mfma_f32_16x16x32_bf16 v[92:95], v[208:211], v[168:171], 0
	v_mfma_f32_16x16x32_bf16 v[92:95], v[212:215], v[172:175], v[92:95]
	v_mfma_f32_16x16x32_bf16 v[88:91], v[216:219], v[168:171], 0
	v_mfma_f32_16x16x32_bf16 v[88:91], v[220:223], v[172:175], v[88:91]
	v_mfma_f32_16x16x32_bf16 v[84:87], v[184:187], v[176:179], 0
	v_mfma_f32_16x16x32_bf16 v[84:87], v[188:191], v[180:183], v[84:87]
	v_mfma_f32_16x16x32_bf16 v[80:83], v[192:195], v[176:179], 0
	v_mfma_f32_16x16x32_bf16 v[80:83], v[196:199], v[180:183], v[80:83]
	v_mfma_f32_16x16x32_bf16 v[76:79], v[208:211], v[176:179], 0
	v_mfma_f32_16x16x32_bf16 v[76:79], v[212:215], v[180:183], v[76:79]
	v_mfma_f32_16x16x32_bf16 v[72:75], v[216:219], v[176:179], 0
	v_mfma_f32_16x16x32_bf16 v[72:75], v[220:223], v[180:183], v[72:75]
	s_barrier
	s_add_i32 s51, s51, s38
	v_lshl_add_u64 v[224:225], s[12:13], 0, v[138:139]
	s_mov_b32 m0, s51
	ds_read_b128 v[150:153], v155 offset:16384
	ds_read_b128 v[156:159], v155 offset:17408
	ds_read_b128 v[160:163], v155 offset:18432
	ds_read_b128 v[164:167], v155 offset:19456
	ds_read_b128 v[168:171], v155 offset:20480
	ds_read_b128 v[172:175], v155 offset:21504
	ds_read_b128 v[176:179], v155 offset:22528
	ds_read_b128 v[180:183], v155 offset:23552
	global_load_lds_dwordx4 v[224:225], off
	s_add_i32 m0, s51, 0x2000
	s_add_u32 s64, s12, 0x80000
	v_lshl_add_u64 v[226:227], s[12:13], 0, v[4:5]
	s_addc_u32 s65, s13, 0
	s_add_i32 s51, s63, s38
	global_load_lds_dwordx4 v[226:227], off
	v_lshl_add_u64 v[228:229], s[64:65], 0, v[138:139]
	s_mov_b32 m0, s51
	v_lshl_add_u64 v[230:231], s[14:15], 0, v[136:137]
	global_load_lds_dwordx4 v[228:229], off
	v_lshl_add_u64 v[228:229], s[64:65], 0, v[4:5]
	s_add_i32 m0, s51, 0x2000
	s_nop 0
	global_load_lds_dwordx4 v[228:229], off
	v_lshl_add_u64 v[228:229], s[14:15], 0, v[140:141]
	s_mov_b32 m0, s39
	s_nop 0
	global_load_lds_dwordx4 v[228:229], off
	s_mov_b32 m0, s40
	s_nop 0
	global_load_lds_dwordx4 v[230:231], off
	s_waitcnt vmcnt(8)
	s_waitcnt lgkmcnt(0)
	s_barrier
	s_waitcnt lgkmcnt(0)
	v_mfma_f32_16x16x32_bf16 v[68:71], v[184:187], v[150:153], 0
	v_mfma_f32_16x16x32_bf16 v[68:71], v[188:191], v[156:159], v[68:71]
	v_mfma_f32_16x16x32_bf16 v[64:67], v[192:195], v[150:153], 0
	v_mfma_f32_16x16x32_bf16 v[64:67], v[196:199], v[156:159], v[64:67]
	v_mfma_f32_16x16x32_bf16 v[60:63], v[208:211], v[150:153], 0
	v_mfma_f32_16x16x32_bf16 v[60:63], v[212:215], v[156:159], v[60:63]
	v_mfma_f32_16x16x32_bf16 v[56:59], v[216:219], v[150:153], 0
	v_mfma_f32_16x16x32_bf16 v[56:59], v[220:223], v[156:159], v[56:59]
	v_mfma_f32_16x16x32_bf16 v[52:55], v[184:187], v[160:163], 0
	v_mfma_f32_16x16x32_bf16 v[52:55], v[188:191], v[164:167], v[52:55]
	v_mfma_f32_16x16x32_bf16 v[48:51], v[192:195], v[160:163], 0
	v_mfma_f32_16x16x32_bf16 v[48:51], v[196:199], v[164:167], v[48:51]
	v_mfma_f32_16x16x32_bf16 v[44:47], v[208:211], v[160:163], 0
	v_mfma_f32_16x16x32_bf16 v[44:47], v[212:215], v[164:167], v[44:47]
	v_mfma_f32_16x16x32_bf16 v[40:43], v[216:219], v[160:163], 0
	v_mfma_f32_16x16x32_bf16 v[40:43], v[220:223], v[164:167], v[40:43]
	v_mfma_f32_16x16x32_bf16 v[36:39], v[184:187], v[168:171], 0
	v_mfma_f32_16x16x32_bf16 v[36:39], v[188:191], v[172:175], v[36:39]
	v_mfma_f32_16x16x32_bf16 v[32:35], v[192:195], v[168:171], 0
	v_mfma_f32_16x16x32_bf16 v[32:35], v[196:199], v[172:175], v[32:35]
	v_mfma_f32_16x16x32_bf16 v[28:31], v[208:211], v[168:171], 0
	v_mfma_f32_16x16x32_bf16 v[28:31], v[212:215], v[172:175], v[28:31]
	v_mfma_f32_16x16x32_bf16 v[24:27], v[216:219], v[168:171], 0
	v_mfma_f32_16x16x32_bf16 v[24:27], v[220:223], v[172:175], v[24:27]
	v_mfma_f32_16x16x32_bf16 v[20:23], v[184:187], v[176:179], 0
	v_mfma_f32_16x16x32_bf16 v[20:23], v[188:191], v[180:183], v[20:23]
	v_mfma_f32_16x16x32_bf16 v[16:19], v[192:195], v[176:179], 0
	v_mfma_f32_16x16x32_bf16 v[16:19], v[196:199], v[180:183], v[16:19]
	v_mfma_f32_16x16x32_bf16 v[12:15], v[208:211], v[176:179], 0
	v_mfma_f32_16x16x32_bf16 v[12:15], v[212:215], v[180:183], v[12:15]
	v_mfma_f32_16x16x32_bf16 v[8:11], v[216:219], v[176:179], 0
	v_mfma_f32_16x16x32_bf16 v[8:11], v[220:223], v[180:183], v[8:11]
	s_barrier
	s_add_i32 s51, 0, 0x18000
	s_add_i32 s63, 0, 0x1c000
	s_add_u32 s14, s14, 0x80000
	v_add_u32_e32 v2, s51, v7
	s_addc_u32 s15, s15, 0
	s_mov_b32 m0, s41
	ds_read_b128 v[150:153], v155 offset:32768
	ds_read_b128 v[156:159], v155 offset:33792
	ds_read_b128 v[160:163], v155 offset:34816
	ds_read_b128 v[164:167], v155 offset:35840
	ds_read_b128 v[168:171], v155 offset:36864
	ds_read_b128 v[172:175], v155 offset:37888
	ds_read_b128 v[176:179], v155 offset:38912
	ds_read_b128 v[180:183], v155 offset:39936
	ds_read_b128 v[184:187], v2
	ds_read_b128 v[188:191], v2 offset:1024
	ds_read_b128 v[192:195], v2 offset:2048
	ds_read_b128 v[196:199], v2 offset:3072
	v_add_u32_e32 v2, s63, v7
	v_lshl_add_u64 v[232:233], s[14:15], 0, v[140:141]
	ds_read_b128 v[208:211], v2
	ds_read_b128 v[212:215], v2 offset:1024
	ds_read_b128 v[216:219], v2 offset:2048
	ds_read_b128 v[220:223], v2 offset:3072
	global_load_lds_dwordx4 v[232:233], off
	v_lshl_add_u64 v[232:233], s[14:15], 0, v[136:137]
	s_mov_b32 m0, s47
	s_nop 0
	global_load_lds_dwordx4 v[232:233], off
	s_waitcnt vmcnt(8)
	s_waitcnt lgkmcnt(0)
	s_barrier
	s_waitcnt lgkmcnt(0)
	v_mfma_f32_16x16x32_bf16 v[132:135], v[184:187], v[150:153], v[132:135]
	v_mfma_f32_16x16x32_bf16 v[132:135], v[188:191], v[156:159], v[132:135]
	v_mfma_f32_16x16x32_bf16 v[128:131], v[192:195], v[150:153], v[128:131]
	v_mfma_f32_16x16x32_bf16 v[128:131], v[196:199], v[156:159], v[128:131]
	v_mfma_f32_16x16x32_bf16 v[124:127], v[208:211], v[150:153], v[124:127]
	v_mfma_f32_16x16x32_bf16 v[124:127], v[212:215], v[156:159], v[124:127]
	v_mfma_f32_16x16x32_bf16 v[120:123], v[216:219], v[150:153], v[120:123]
	v_mfma_f32_16x16x32_bf16 v[120:123], v[220:223], v[156:159], v[120:123]
	v_mfma_f32_16x16x32_bf16 v[116:119], v[184:187], v[160:163], v[116:119]
	v_mfma_f32_16x16x32_bf16 v[116:119], v[188:191], v[164:167], v[116:119]
	v_mfma_f32_16x16x32_bf16 v[112:115], v[192:195], v[160:163], v[112:115]
	v_mfma_f32_16x16x32_bf16 v[112:115], v[196:199], v[164:167], v[112:115]
	v_mfma_f32_16x16x32_bf16 v[108:111], v[208:211], v[160:163], v[108:111]
	v_mfma_f32_16x16x32_bf16 v[108:111], v[212:215], v[164:167], v[108:111]
	v_mfma_f32_16x16x32_bf16 v[104:107], v[216:219], v[160:163], v[104:107]
	v_mfma_f32_16x16x32_bf16 v[104:107], v[220:223], v[164:167], v[104:107]
	v_mfma_f32_16x16x32_bf16 v[100:103], v[184:187], v[168:171], v[100:103]
	v_mfma_f32_16x16x32_bf16 v[100:103], v[188:191], v[172:175], v[100:103]
	v_mfma_f32_16x16x32_bf16 v[96:99], v[192:195], v[168:171], v[96:99]
	v_mfma_f32_16x16x32_bf16 v[96:99], v[196:199], v[172:175], v[96:99]
	v_mfma_f32_16x16x32_bf16 v[92:95], v[208:211], v[168:171], v[92:95]
	v_mfma_f32_16x16x32_bf16 v[92:95], v[212:215], v[172:175], v[92:95]
	v_mfma_f32_16x16x32_bf16 v[88:91], v[216:219], v[168:171], v[88:91]
	v_mfma_f32_16x16x32_bf16 v[88:91], v[220:223], v[172:175], v[88:91]
	v_mfma_f32_16x16x32_bf16 v[84:87], v[184:187], v[176:179], v[84:87]
	v_mfma_f32_16x16x32_bf16 v[84:87], v[188:191], v[180:183], v[84:87]
	v_mfma_f32_16x16x32_bf16 v[80:83], v[192:195], v[176:179], v[80:83]
	v_mfma_f32_16x16x32_bf16 v[80:83], v[196:199], v[180:183], v[80:83]
	v_mfma_f32_16x16x32_bf16 v[76:79], v[208:211], v[176:179], v[76:79]
	v_mfma_f32_16x16x32_bf16 v[76:79], v[212:215], v[180:183], v[76:79]
	v_mfma_f32_16x16x32_bf16 v[72:75], v[216:219], v[176:179], v[72:75]
	v_mfma_f32_16x16x32_bf16 v[72:75], v[220:223], v[180:183], v[72:75]
	s_barrier
	s_add_i32 s14, s51, s38
	v_lshl_add_u64 v[224:225], v[224:225], 0, s[0:1]
	s_mov_b32 m0, s14
	ds_read_b128 v[150:153], v155 offset:49152
	ds_read_b128 v[156:159], v155 offset:50176
	ds_read_b128 v[160:163], v155 offset:51200
	ds_read_b128 v[164:167], v155 offset:52224
	ds_read_b128 v[168:171], v155 offset:53248
	ds_read_b128 v[172:175], v155 offset:54272
	ds_read_b128 v[176:179], v155 offset:55296
	ds_read_b128 v[180:183], v155 offset:56320
	global_load_lds_dwordx4 v[224:225], off
	s_add_i32 m0, s14, 0x2000
	s_add_u32 s12, s12, 0x80080
	v_lshl_add_u64 v[224:225], v[226:227], 0, s[0:1]
	s_addc_u32 s13, s13, 0
	s_add_i32 s14, s63, s38
	global_load_lds_dwordx4 v[224:225], off
	v_lshl_add_u64 v[224:225], s[12:13], 0, v[138:139]
	s_mov_b32 m0, s14
	s_nop 0
	global_load_lds_dwordx4 v[224:225], off
	v_lshl_add_u64 v[224:225], s[12:13], 0, v[4:5]
	s_add_i32 m0, s14, 0x2000
	s_nop 0
	global_load_lds_dwordx4 v[224:225], off
	v_lshl_add_u64 v[224:225], v[228:229], 0, s[0:1]
	s_mov_b32 m0, s60
	s_nop 0
	global_load_lds_dwordx4 v[224:225], off
	v_lshl_add_u64 v[224:225], v[230:231], 0, s[0:1]
	s_mov_b32 m0, s61
	s_nop 0
	global_load_lds_dwordx4 v[224:225], off
	s_waitcnt vmcnt(8)
	s_waitcnt lgkmcnt(0)
	s_barrier
	s_waitcnt lgkmcnt(0)
	v_mfma_f32_16x16x32_bf16 v[68:71], v[184:187], v[150:153], v[68:71]
	v_mfma_f32_16x16x32_bf16 v[68:71], v[188:191], v[156:159], v[68:71]
	v_mfma_f32_16x16x32_bf16 v[64:67], v[192:195], v[150:153], v[64:67]
	v_mfma_f32_16x16x32_bf16 v[64:67], v[196:199], v[156:159], v[64:67]
	v_mfma_f32_16x16x32_bf16 v[60:63], v[208:211], v[150:153], v[60:63]
	v_mfma_f32_16x16x32_bf16 v[60:63], v[212:215], v[156:159], v[60:63]
	v_mfma_f32_16x16x32_bf16 v[56:59], v[216:219], v[150:153], v[56:59]
	v_mfma_f32_16x16x32_bf16 v[56:59], v[220:223], v[156:159], v[56:59]
	v_mfma_f32_16x16x32_bf16 v[52:55], v[184:187], v[160:163], v[52:55]
	v_mfma_f32_16x16x32_bf16 v[52:55], v[188:191], v[164:167], v[52:55]
	v_mfma_f32_16x16x32_bf16 v[48:51], v[192:195], v[160:163], v[48:51]
	v_mfma_f32_16x16x32_bf16 v[48:51], v[196:199], v[164:167], v[48:51]
	v_mfma_f32_16x16x32_bf16 v[44:47], v[208:211], v[160:163], v[44:47]
	v_mfma_f32_16x16x32_bf16 v[44:47], v[212:215], v[164:167], v[44:47]
	v_mfma_f32_16x16x32_bf16 v[40:43], v[216:219], v[160:163], v[40:43]
	v_mfma_f32_16x16x32_bf16 v[40:43], v[220:223], v[164:167], v[40:43]
	v_mfma_f32_16x16x32_bf16 v[36:39], v[184:187], v[168:171], v[36:39]
	v_mfma_f32_16x16x32_bf16 v[36:39], v[188:191], v[172:175], v[36:39]
	v_mfma_f32_16x16x32_bf16 v[32:35], v[192:195], v[168:171], v[32:35]
	v_mfma_f32_16x16x32_bf16 v[32:35], v[196:199], v[172:175], v[32:35]
	v_mfma_f32_16x16x32_bf16 v[28:31], v[208:211], v[168:171], v[28:31]
	v_mfma_f32_16x16x32_bf16 v[28:31], v[212:215], v[172:175], v[28:31]
	v_mfma_f32_16x16x32_bf16 v[24:27], v[216:219], v[168:171], v[24:27]
	v_mfma_f32_16x16x32_bf16 v[24:27], v[220:223], v[172:175], v[24:27]
	v_mfma_f32_16x16x32_bf16 v[20:23], v[184:187], v[176:179], v[20:23]
	v_mfma_f32_16x16x32_bf16 v[20:23], v[188:191], v[180:183], v[20:23]
	v_mfma_f32_16x16x32_bf16 v[16:19], v[192:195], v[176:179], v[16:19]
	v_mfma_f32_16x16x32_bf16 v[16:19], v[196:199], v[180:183], v[16:19]
	v_mfma_f32_16x16x32_bf16 v[12:15], v[208:211], v[176:179], v[12:15]
	v_mfma_f32_16x16x32_bf16 v[12:15], v[212:215], v[180:183], v[12:15]
	v_mfma_f32_16x16x32_bf16 v[8:11], v[216:219], v[176:179], v[8:11]
	v_mfma_f32_16x16x32_bf16 v[8:11], v[220:223], v[180:183], v[8:11]
	s_barrier
	s_add_i32 s50, s50, 2
	s_add_u32 s44, s44, 0x100
	s_addc_u32 s45, s45, 0
	s_add_u32 s33, s33, 0x100
	s_addc_u32 s43, s43, 0
	s_cmp_gt_u32 s50, 29
	s_cbranch_scc0 .LBB0_986
	s_branch .Lpeelb1_exit

.Lpeelb1_exit:
	s_and_b64 vcc, exec, s[10:11]
	s_cbranch_vccz .LBB0_1031
	s_barrier
	s_cmp_gt_i32 s35, 15
	s_mov_b64 s[12:13], -1
	s_cbranch_scc1 .LBB0_1032

.LBB0_1481:
	s_add_u32 s50, s12, 0x100
	s_addc_u32 s51, s13, 0
	s_add_u32 s14, s26, 0x100
	v_mov_b32_e32 v8, 0
	s_addc_u32 s15, s27, 0
	s_mov_b32 s12, 0
	s_add_i32 s26, s12, 2
	s_cmp_eq_u32 s57, s12
	s_cselect_b32 s13, s43, s51
	s_cselect_b32 s12, s42, s50
	s_cselect_b32 s65, s45, s15
	s_cselect_b32 s64, s44, s14
	s_add_i32 s27, 0, 0x10000
	s_movk_i32 s66, 0xff80
	v_add_u32_e32 v121, s27, v7
	s_add_i32 s63, 0, 0x14000
	v_lshl_add_u64 v[178:179], s[50:51], 0, v[108:109]
	s_mov_b32 s67, -1
	ds_read_b128 v[110:113], v119
	ds_read_b128 v[114:117], v119 offset:1024
	ds_read_b128 v[122:125], v119 offset:2048
	ds_read_b128 v[126:129], v119 offset:3072
	ds_read_b128 v[130:133], v119 offset:4096
	ds_read_b128 v[134:137], v119 offset:5120
	ds_read_b128 v[138:141], v119 offset:6144
	ds_read_b128 v[142:145], v119 offset:7168
	ds_read_b128 v[146:149], v121
	ds_read_b128 v[150:153], v121 offset:1024
	ds_read_b128 v[154:157], v121 offset:2048
	ds_read_b128 v[158:161], v121 offset:3072
	v_add_u32_e32 v121, s63, v7
	v_lshl_add_u64 v[178:179], v[178:179], 0, s[66:67]
	s_add_i32 m0, s39, 0xc000
	ds_read_b128 v[162:165], v121
	ds_read_b128 v[166:169], v121 offset:1024
	ds_read_b128 v[170:173], v121 offset:2048
	ds_read_b128 v[174:177], v121 offset:3072
	global_load_lds_dwordx4 v[178:179], off
	s_waitcnt vmcnt(7)
	s_waitcnt lgkmcnt(0)
	s_barrier
	s_waitcnt lgkmcnt(0)
	v_mfma_f32_16x16x32_bf16 v[100:103], v[146:149], v[110:113], 0
	v_mfma_f32_16x16x32_bf16 v[100:103], v[150:153], v[114:117], v[100:103]
	v_mfma_f32_16x16x32_bf16 v[96:99], v[154:157], v[110:113], 0
	v_mfma_f32_16x16x32_bf16 v[96:99], v[158:161], v[114:117], v[96:99]
	v_mfma_f32_16x16x32_bf16 v[88:91], v[162:165], v[110:113], 0
	v_mfma_f32_16x16x32_bf16 v[88:91], v[166:169], v[114:117], v[88:91]
	v_mfma_f32_16x16x32_bf16 v[84:87], v[170:173], v[110:113], 0
	v_mfma_f32_16x16x32_bf16 v[84:87], v[174:177], v[114:117], v[84:87]
	v_mfma_f32_16x16x32_bf16 v[92:95], v[146:149], v[122:125], 0
	v_mfma_f32_16x16x32_bf16 v[92:95], v[150:153], v[126:129], v[92:95]
	v_mfma_f32_16x16x32_bf16 v[80:83], v[154:157], v[122:125], 0
	v_mfma_f32_16x16x32_bf16 v[80:83], v[158:161], v[126:129], v[80:83]
	v_mfma_f32_16x16x32_bf16 v[76:79], v[162:165], v[122:125], 0
	v_mfma_f32_16x16x32_bf16 v[76:79], v[166:169], v[126:129], v[76:79]
	v_mfma_f32_16x16x32_bf16 v[68:71], v[170:173], v[122:125], 0
	v_mfma_f32_16x16x32_bf16 v[68:71], v[174:177], v[126:129], v[68:71]
	v_mfma_f32_16x16x32_bf16 v[72:75], v[146:149], v[130:133], 0
	v_mfma_f32_16x16x32_bf16 v[72:75], v[150:153], v[134:137], v[72:75]
	v_mfma_f32_16x16x32_bf16 v[64:67], v[154:157], v[130:133], 0
	v_mfma_f32_16x16x32_bf16 v[64:67], v[158:161], v[134:137], v[64:67]
	v_mfma_f32_16x16x32_bf16 v[60:63], v[162:165], v[130:133], 0
	v_mfma_f32_16x16x32_bf16 v[60:63], v[166:169], v[134:137], v[60:63]
	v_mfma_f32_16x16x32_bf16 v[52:55], v[170:173], v[130:133], 0
	v_mfma_f32_16x16x32_bf16 v[52:55], v[174:177], v[134:137], v[52:55]
	v_mfma_f32_16x16x32_bf16 v[56:59], v[146:149], v[138:141], 0
	v_mfma_f32_16x16x32_bf16 v[56:59], v[150:153], v[142:145], v[56:59]
	v_mfma_f32_16x16x32_bf16 v[48:51], v[154:157], v[138:141], 0
	v_mfma_f32_16x16x32_bf16 v[48:51], v[158:161], v[142:145], v[48:51]
	v_mfma_f32_16x16x32_bf16 v[44:47], v[162:165], v[138:141], 0
	v_mfma_f32_16x16x32_bf16 v[44:47], v[166:169], v[142:145], v[44:47]
	v_mfma_f32_16x16x32_bf16 v[40:43], v[170:173], v[138:141], 0
	v_mfma_f32_16x16x32_bf16 v[40:43], v[174:177], v[142:145], v[40:43]
	s_barrier
	s_add_i32 s27, s27, s22
	v_lshl_add_u64 v[178:179], s[64:65], 0, v[2:3]
	s_mov_b32 m0, s27
	ds_read_b128 v[110:113], v120 offset:16384
	ds_read_b128 v[114:117], v120 offset:17408
	ds_read_b128 v[122:125], v120 offset:18432
	ds_read_b128 v[126:129], v120 offset:19456
	global_load_lds_dwordx4 v[178:179], off
	s_add_i32 m0, s27, 0x2000
	v_lshl_add_u64 v[180:181], s[64:65], 0, v[4:5]
	s_add_u32 s64, s64, s90
	s_addc_u32 s65, s65, 0
	s_add_i32 s27, s63, s22
	global_load_lds_dwordx4 v[180:181], off
	v_lshl_add_u64 v[182:183], s[64:65], 0, v[2:3]
	s_mov_b32 m0, s27
	v_lshl_add_u64 v[184:185], s[64:65], 0, v[4:5]
	global_load_lds_dwordx4 v[182:183], off
	s_add_i32 m0, s27, 0x2000
	v_lshl_add_u64 v[186:187], s[12:13], 0, v[106:107]
	global_load_lds_dwordx4 v[184:185], off
	s_mov_b32 m0, s39
	v_lshl_add_u64 v[188:189], s[12:13], 0, v[104:105]
	global_load_lds_dwordx4 v[186:187], off
	s_mov_b32 m0, s40
	s_nop 0
	global_load_lds_dwordx4 v[188:189], off
	s_waitcnt vmcnt(7)
	s_waitcnt lgkmcnt(0)
	s_barrier
	s_waitcnt lgkmcnt(0)
	v_mfma_f32_16x16x32_bf16 v[36:39], v[146:149], v[110:113], 0
	v_mfma_f32_16x16x32_bf16 v[36:39], v[150:153], v[114:117], v[36:39]
	v_mfma_f32_16x16x32_bf16 v[32:35], v[154:157], v[110:113], 0
	v_mfma_f32_16x16x32_bf16 v[32:35], v[158:161], v[114:117], v[32:35]
	v_mfma_f32_16x16x32_bf16 v[28:31], v[162:165], v[110:113], 0
	v_mfma_f32_16x16x32_bf16 v[28:31], v[166:169], v[114:117], v[28:31]
	v_mfma_f32_16x16x32_bf16 v[24:27], v[170:173], v[110:113], 0
	v_mfma_f32_16x16x32_bf16 v[24:27], v[174:177], v[114:117], v[24:27]
	v_mfma_f32_16x16x32_bf16 v[20:23], v[146:149], v[122:125], 0
	v_mfma_f32_16x16x32_bf16 v[20:23], v[150:153], v[126:129], v[20:23]
	v_mfma_f32_16x16x32_bf16 v[16:19], v[154:157], v[122:125], 0
	v_mfma_f32_16x16x32_bf16 v[16:19], v[158:161], v[126:129], v[16:19]
	v_mfma_f32_16x16x32_bf16 v[12:15], v[162:165], v[122:125], 0
	v_mfma_f32_16x16x32_bf16 v[12:15], v[166:169], v[126:129], v[12:15]
	v_mfma_f32_16x16x32_bf16 v[8:11], v[170:173], v[122:125], 0
	v_mfma_f32_16x16x32_bf16 v[8:11], v[174:177], v[126:129], v[8:11]
	s_barrier
	s_add_i32 s27, 0, 0x18000
	s_add_i32 s63, 0, 0x1c000
	s_add_u32 s12, s12, s90
	v_add_u32_e32 v121, s27, v7
	s_addc_u32 s13, s13, 0
	ds_read_b128 v[110:113], v119 offset:32768
	ds_read_b128 v[114:117], v119 offset:33792
	ds_read_b128 v[122:125], v119 offset:34816
	ds_read_b128 v[126:129], v119 offset:35840
	ds_read_b128 v[130:133], v119 offset:36864
	ds_read_b128 v[134:137], v119 offset:37888
	ds_read_b128 v[138:141], v119 offset:38912
	ds_read_b128 v[142:145], v119 offset:39936
	ds_read_b128 v[146:149], v121
	ds_read_b128 v[150:153], v121 offset:1024
	ds_read_b128 v[154:157], v121 offset:2048
	ds_read_b128 v[158:161], v121 offset:3072
	v_add_u32_e32 v121, s63, v7
	v_lshl_add_u64 v[190:191], s[12:13], 0, v[106:107]
	s_mov_b32 m0, s41
	ds_read_b128 v[162:165], v121
	ds_read_b128 v[166:169], v121 offset:1024
	ds_read_b128 v[170:173], v121 offset:2048
	ds_read_b128 v[174:177], v121 offset:3072
	global_load_lds_dwordx4 v[190:191], off
	s_waitcnt vmcnt(7)
	s_waitcnt lgkmcnt(0)
	s_barrier
	s_waitcnt lgkmcnt(0)
	v_mfma_f32_16x16x32_bf16 v[100:103], v[146:149], v[110:113], v[100:103]
	v_mfma_f32_16x16x32_bf16 v[100:103], v[150:153], v[114:117], v[100:103]
	v_mfma_f32_16x16x32_bf16 v[96:99], v[154:157], v[110:113], v[96:99]
	v_mfma_f32_16x16x32_bf16 v[96:99], v[158:161], v[114:117], v[96:99]
	v_mfma_f32_16x16x32_bf16 v[88:91], v[162:165], v[110:113], v[88:91]
	v_mfma_f32_16x16x32_bf16 v[88:91], v[166:169], v[114:117], v[88:91]
	v_mfma_f32_16x16x32_bf16 v[84:87], v[170:173], v[110:113], v[84:87]
	v_mfma_f32_16x16x32_bf16 v[84:87], v[174:177], v[114:117], v[84:87]
	v_mfma_f32_16x16x32_bf16 v[92:95], v[146:149], v[122:125], v[92:95]
	v_mfma_f32_16x16x32_bf16 v[92:95], v[150:153], v[126:129], v[92:95]
	v_mfma_f32_16x16x32_bf16 v[80:83], v[154:157], v[122:125], v[80:83]
	v_mfma_f32_16x16x32_bf16 v[80:83], v[158:161], v[126:129], v[80:83]
	v_mfma_f32_16x16x32_bf16 v[76:79], v[162:165], v[122:125], v[76:79]
	v_mfma_f32_16x16x32_bf16 v[76:79], v[166:169], v[126:129], v[76:79]
	v_mfma_f32_16x16x32_bf16 v[68:71], v[170:173], v[122:125], v[68:71]
	v_mfma_f32_16x16x32_bf16 v[68:71], v[174:177], v[126:129], v[68:71]
	v_mfma_f32_16x16x32_bf16 v[72:75], v[146:149], v[130:133], v[72:75]
	v_mfma_f32_16x16x32_bf16 v[72:75], v[150:153], v[134:137], v[72:75]
	v_mfma_f32_16x16x32_bf16 v[64:67], v[154:157], v[130:133], v[64:67]
	v_mfma_f32_16x16x32_bf16 v[64:67], v[158:161], v[134:137], v[64:67]
	v_mfma_f32_16x16x32_bf16 v[60:63], v[162:165], v[130:133], v[60:63]
	v_mfma_f32_16x16x32_bf16 v[60:63], v[166:169], v[134:137], v[60:63]
	v_mfma_f32_16x16x32_bf16 v[52:55], v[170:173], v[130:133], v[52:55]
	v_mfma_f32_16x16x32_bf16 v[52:55], v[174:177], v[134:137], v[52:55]
	v_mfma_f32_16x16x32_bf16 v[56:59], v[146:149], v[138:141], v[56:59]
	v_mfma_f32_16x16x32_bf16 v[56:59], v[150:153], v[142:145], v[56:59]
	v_mfma_f32_16x16x32_bf16 v[48:51], v[154:157], v[138:141], v[48:51]
	v_mfma_f32_16x16x32_bf16 v[48:51], v[158:161], v[142:145], v[48:51]
	v_mfma_f32_16x16x32_bf16 v[44:47], v[162:165], v[138:141], v[44:47]
	v_mfma_f32_16x16x32_bf16 v[44:47], v[166:169], v[142:145], v[44:47]
	v_mfma_f32_16x16x32_bf16 v[40:43], v[170:173], v[138:141], v[40:43]
	v_mfma_f32_16x16x32_bf16 v[40:43], v[174:177], v[142:145], v[40:43]
	s_barrier
	s_add_i32 s12, s27, s22
	v_lshl_add_u64 v[130:131], v[178:179], 0, s[0:1]
	s_mov_b32 m0, s12
	ds_read_b128 v[110:113], v120 offset:49152
	ds_read_b128 v[114:117], v120 offset:50176
	ds_read_b128 v[122:125], v120 offset:51200
	ds_read_b128 v[126:129], v120 offset:52224
	global_load_lds_dwordx4 v[130:131], off
	v_lshl_add_u64 v[130:131], v[180:181], 0, s[0:1]
	s_add_i32 m0, s12, 0x2000
	s_add_i32 s12, s63, s22
	global_load_lds_dwordx4 v[130:131], off
	v_lshl_add_u64 v[130:131], v[182:183], 0, s[0:1]
	s_mov_b32 m0, s12
	s_nop 0
	global_load_lds_dwordx4 v[130:131], off
	v_lshl_add_u64 v[130:131], v[184:185], 0, s[0:1]
	s_add_i32 m0, s12, 0x2000
	s_nop 0
	global_load_lds_dwordx4 v[130:131], off
	v_lshl_add_u64 v[130:131], v[186:187], 0, s[0:1]
	s_mov_b32 m0, s53
	s_nop 0
	global_load_lds_dwordx4 v[130:131], off
	v_lshl_add_u64 v[130:131], v[188:189], 0, s[0:1]
	s_mov_b32 m0, s54
	s_nop 0
	global_load_lds_dwordx4 v[130:131], off
	s_waitcnt vmcnt(7)
	s_waitcnt lgkmcnt(0)
	s_barrier
	s_waitcnt lgkmcnt(0)
	v_mfma_f32_16x16x32_bf16 v[36:39], v[146:149], v[110:113], v[36:39]
	v_mfma_f32_16x16x32_bf16 v[36:39], v[150:153], v[114:117], v[36:39]
	v_mfma_f32_16x16x32_bf16 v[32:35], v[154:157], v[110:113], v[32:35]
	v_mfma_f32_16x16x32_bf16 v[32:35], v[158:161], v[114:117], v[32:35]
	v_mfma_f32_16x16x32_bf16 v[28:31], v[162:165], v[110:113], v[28:31]
	v_mfma_f32_16x16x32_bf16 v[28:31], v[166:169], v[114:117], v[28:31]
	v_mfma_f32_16x16x32_bf16 v[24:27], v[170:173], v[110:113], v[24:27]
	v_mfma_f32_16x16x32_bf16 v[24:27], v[174:177], v[114:117], v[24:27]
	v_mfma_f32_16x16x32_bf16 v[20:23], v[146:149], v[122:125], v[20:23]
	v_mfma_f32_16x16x32_bf16 v[20:23], v[150:153], v[126:129], v[20:23]
	v_mfma_f32_16x16x32_bf16 v[16:19], v[154:157], v[122:125], v[16:19]
	v_mfma_f32_16x16x32_bf16 v[16:19], v[158:161], v[126:129], v[16:19]
	v_mfma_f32_16x16x32_bf16 v[12:15], v[162:165], v[122:125], v[12:15]
	v_mfma_f32_16x16x32_bf16 v[12:15], v[166:169], v[126:129], v[12:15]
	v_mfma_f32_16x16x32_bf16 v[8:11], v[170:173], v[122:125], v[8:11]
	v_mfma_f32_16x16x32_bf16 v[8:11], v[174:177], v[126:129], v[8:11]
	s_barrier
	s_add_u32 s50, s50, 0x100
	s_addc_u32 s51, s51, 0
	s_add_u32 s14, s14, 0x100
	s_addc_u32 s15, s15, 0
	s_cmp_ge_u32 s26, s55
	s_mov_b32 s12, s26
	s_cbranch_scc0 .LBB0_1482
	s_branch .Lpeelb2_exit

.Lpeelb2_exit:
	s_and_b64 vcc, exec, s[36:37]
	s_cbranch_vccz .LBB0_1485
	s_barrier
